# phase-0 weight transposes: the 32 per-element loads of each tile issued together with one wait instead of load-wait-LDSwrite 32 times (on top of the sample streaming loop rewrite)
# speedup vs baseline: 1.0435x; 1.0435x over previous
.LBB0_10:
	v_cmp_lt_i32_e32 vcc, s49, v78
	s_and_saveexec_b64 s[36:37], vcc
	s_xor_b64 s[36:37], exec, s[36:37]
	s_cbranch_execz .LBB0_32
	v_cmp_lt_u32_e32 vcc, s50, v78
	s_and_saveexec_b64 s[38:39], vcc
	s_xor_b64 s[38:39], exec, s[38:39]
	s_cbranch_execz .LBB0_29
	v_cmp_lt_u32_e32 vcc, s51, v78
	s_and_saveexec_b64 s[40:41], vcc
	s_xor_b64 s[40:41], exec, s[40:41]
	s_cbranch_execz .LBB0_26
	v_cmp_lt_u32_e32 vcc, s53, v78
	s_and_saveexec_b64 s[42:43], vcc
	s_xor_b64 s[42:43], exec, s[42:43]
	s_cbranch_execz .LBB0_23
	v_cmp_lt_u32_e32 vcc, s54, v78
	s_and_saveexec_b64 s[44:45], vcc
	s_xor_b64 s[44:45], exec, s[44:45]
	s_cbranch_execz .LBB0_20
	v_cmp_lt_u32_e32 vcc, s55, v78
	s_and_saveexec_b64 s[46:47], vcc
	s_xor_b64 s[46:47], exec, s[46:47]
	s_cbranch_execz .LBB0_17
	v_and_b32_e32 v25, 0x3e0, v74
	v_and_b32_e32 v24, 0x1ffc0, v77
	v_or_b32_e32 v2, v25, v26
	v_or_b32_e32 v22, v24, v19
	v_lshlrev_b32_e32 v79, 2, v2
	v_lshl_or_b32 v2, v22, 12, v79
	v_lshl_add_u64 v[22:23], s[26:27], 0, v[2:3]
	global_load_dword v126, v[22:23], off
	v_or_b32_e32 v2, v24, v29
	v_lshl_or_b32 v2, v2, 12, v79
	v_lshl_add_u64 v[22:23], s[26:27], 0, v[2:3]
	v_or_b32_e32 v2, v24, v30
	v_lshl_or_b32 v2, v2, 12, v79
	v_or_b32_e32 v86, v25, v71
	global_load_dword v128, v[22:23], off
	v_lshl_add_u64 v[22:23], s[26:27], 0, v[2:3]
	v_or_b32_e32 v2, v24, v31
	v_lshl_or_b32 v2, v2, 12, v79
	global_load_dword v129, v[22:23], off
	v_lshl_add_u64 v[22:23], s[26:27], 0, v[2:3]
	v_or_b32_e32 v2, v24, v32
	v_lshl_or_b32 v2, v2, 12, v79
	global_load_dword v130, v[22:23], off
	v_lshl_add_u64 v[22:23], s[26:27], 0, v[2:3]
	v_or_b32_e32 v2, v24, v33
	v_lshl_or_b32 v2, v2, 12, v79
	global_load_dword v131, v[22:23], off
	v_lshl_add_u64 v[22:23], s[26:27], 0, v[2:3]
	v_or_b32_e32 v2, v24, v34
	v_lshl_or_b32 v2, v2, 12, v79
	global_load_dword v132, v[22:23], off
	v_lshl_add_u64 v[22:23], s[26:27], 0, v[2:3]
	v_or_b32_e32 v2, v24, v36
	v_lshl_or_b32 v2, v2, 12, v79
	global_load_dword v133, v[22:23], off
	v_lshl_add_u64 v[22:23], s[26:27], 0, v[2:3]
	v_or_b32_e32 v2, v24, v37
	v_lshl_or_b32 v2, v2, 12, v79
	global_load_dword v135, v[22:23], off
	v_lshl_add_u64 v[22:23], s[26:27], 0, v[2:3]
	v_or_b32_e32 v2, v24, v38
	v_lshl_or_b32 v2, v2, 12, v79
	global_load_dword v136, v[22:23], off
	v_lshl_add_u64 v[22:23], s[26:27], 0, v[2:3]
	v_or_b32_e32 v2, v24, v39
	v_lshl_or_b32 v2, v2, 12, v79
	global_load_dword v137, v[22:23], off
	v_lshl_add_u64 v[22:23], s[26:27], 0, v[2:3]
	v_or_b32_e32 v2, v24, v40
	v_lshl_or_b32 v2, v2, 12, v79
	global_load_dword v138, v[22:23], off
	v_lshl_add_u64 v[22:23], s[26:27], 0, v[2:3]
	v_or_b32_e32 v2, v24, v41
	v_lshl_or_b32 v2, v2, 12, v79
	global_load_dword v139, v[22:23], off
	v_lshl_add_u64 v[22:23], s[26:27], 0, v[2:3]
	v_or_b32_e32 v2, v24, v43
	v_lshl_or_b32 v2, v2, 12, v79
	global_load_dword v140, v[22:23], off
	v_lshl_add_u64 v[22:23], s[26:27], 0, v[2:3]
	v_or_b32_e32 v2, v24, v46
	v_lshl_or_b32 v2, v2, 12, v79
	global_load_dword v142, v[22:23], off
	v_lshl_add_u64 v[22:23], s[26:27], 0, v[2:3]
	v_or_b32_e32 v2, v24, v48
	v_lshl_or_b32 v2, v2, 12, v79
	global_load_dword v143, v[22:23], off
	v_lshl_add_u64 v[22:23], s[26:27], 0, v[2:3]
	v_or_b32_e32 v2, v24, v49
	v_lshl_or_b32 v2, v2, 12, v79
	global_load_dword v144, v[22:23], off
	v_lshl_add_u64 v[22:23], s[26:27], 0, v[2:3]
	v_or_b32_e32 v2, v24, v50
	v_lshl_or_b32 v2, v2, 12, v79
	global_load_dword v145, v[22:23], off
	v_lshl_add_u64 v[22:23], s[26:27], 0, v[2:3]
	v_or_b32_e32 v2, v24, v52
	v_lshl_or_b32 v2, v2, 12, v79
	global_load_dword v146, v[22:23], off
	v_lshl_add_u64 v[22:23], s[26:27], 0, v[2:3]
	v_or_b32_e32 v2, v24, v54
	v_lshl_or_b32 v2, v2, 12, v79
	global_load_dword v147, v[22:23], off
	v_lshl_add_u64 v[22:23], s[26:27], 0, v[2:3]
	v_or_b32_e32 v2, v24, v55
	v_lshl_or_b32 v2, v2, 12, v79
	global_load_dword v149, v[22:23], off
	v_lshl_add_u64 v[22:23], s[26:27], 0, v[2:3]
	v_or_b32_e32 v2, v24, v56
	v_lshl_or_b32 v2, v2, 12, v79
	global_load_dword v150, v[22:23], off
	v_lshl_add_u64 v[22:23], s[26:27], 0, v[2:3]
	v_or_b32_e32 v2, v24, v57
	v_lshl_or_b32 v2, v2, 12, v79
	global_load_dword v151, v[22:23], off
	v_lshl_add_u64 v[22:23], s[26:27], 0, v[2:3]
	v_or_b32_e32 v2, v24, v58
	v_lshl_or_b32 v2, v2, 12, v79
	global_load_dword v152, v[22:23], off
	v_lshl_add_u64 v[22:23], s[26:27], 0, v[2:3]
	v_or_b32_e32 v2, v24, v59
	v_lshl_or_b32 v2, v2, 12, v79
	global_load_dword v153, v[22:23], off
	v_lshl_add_u64 v[22:23], s[26:27], 0, v[2:3]
	v_or_b32_e32 v2, v24, v61
	v_lshl_or_b32 v2, v2, 12, v79
	global_load_dword v154, v[22:23], off
	v_lshl_add_u64 v[22:23], s[26:27], 0, v[2:3]
	v_or_b32_e32 v2, v24, v62
	v_lshl_or_b32 v2, v2, 12, v79
	global_load_dword v156, v[22:23], off
	v_lshl_add_u64 v[22:23], s[26:27], 0, v[2:3]
	v_or_b32_e32 v2, v24, v63
	v_lshl_or_b32 v2, v2, 12, v79
	global_load_dword v157, v[22:23], off
	v_lshl_add_u64 v[22:23], s[26:27], 0, v[2:3]
	v_or_b32_e32 v2, v24, v64
	v_lshl_or_b32 v2, v2, 12, v79
	global_load_dword v158, v[22:23], off
	v_lshl_add_u64 v[22:23], s[26:27], 0, v[2:3]
	v_or_b32_e32 v2, v24, v65
	v_lshl_or_b32 v2, v2, 12, v79
	global_load_dword v159, v[22:23], off
	v_lshl_add_u64 v[22:23], s[26:27], 0, v[2:3]
	v_or_b32_e32 v2, v24, v66
	v_lshl_or_b32 v2, v2, 12, v79
	global_load_dword v160, v[22:23], off
	v_lshl_add_u64 v[22:23], s[26:27], 0, v[2:3]
	v_or_b32_e32 v2, v24, v67
	v_lshl_or_b32 v2, v2, 12, v79
	v_or_b32_e32 v79, v25, v70
	global_load_dword v161, v[22:23], off
	v_lshl_add_u64 v[22:23], s[26:27], 0, v[2:3]
	v_lshlrev_b32_e32 v2, 1, v24
	global_load_dword v162, v[22:23], off
	s_waitcnt vmcnt(0) lgkmcnt(0)
	v_add_u32_e32 v127, v27, v28
	v_add_u32_e32 v155, v27, v60
	ds_write_b32 v127, v126
	ds_write_b32 v127, v128 offset:264
	ds_write_b32 v127, v129 offset:528
	ds_write_b32 v127, v130 offset:792
	ds_write_b32 v127, v131 offset:1056
	ds_write_b32 v127, v132 offset:1320
	v_add_u32_e32 v134, v27, v35
	ds_write_b32 v134, v133
	ds_write_b32 v134, v135 offset:264
	ds_write_b32 v134, v136 offset:528
	ds_write_b32 v134, v137 offset:792
	ds_write_b32 v134, v138 offset:1056
	ds_write_b32 v134, v139 offset:1320
	v_add_u32_e32 v141, v27, v42
	ds_write_b32 v141, v140
	ds_write_b32 v141, v142 offset:264
	ds_write_b32 v141, v143 offset:528
	ds_write_b32 v141, v144 offset:792
	ds_write_b32 v141, v145 offset:1056
	ds_write_b32 v141, v146 offset:1320
	v_add_u32_e32 v148, v27, v53
	ds_write_b32 v148, v147
	ds_write_b32 v148, v149 offset:264
	ds_write_b32 v148, v150 offset:528
	ds_write_b32 v148, v151 offset:792
	ds_write_b32 v148, v152 offset:1056
	ds_write_b32 v148, v153 offset:1320
	ds_write_b32 v155, v154
	ds_write_b32 v155, v156 offset:264
	ds_write_b32 v155, v157 offset:528
	ds_write_b32 v155, v158 offset:792
	ds_write_b32 v155, v159 offset:1056
	ds_write_b32 v155, v160 offset:1320
	ds_write_b32 v155, v161 offset:1584
	ds_write_b32 v155, v162 offset:1848
	v_or_b32_e32 v23, v25, v68
	v_lshl_add_u64 v[80:81], v[8:9], 0, v[2:3]
	v_lshlrev_b32_e32 v2, 12, v23
	v_lshl_add_u64 v[82:83], v[80:81], 0, v[2:3]
	v_lshlrev_b32_e32 v2, 12, v79
	v_or_b32_e32 v25, v25, v72
	v_lshl_add_u64 v[84:85], v[80:81], 0, v[2:3]
	v_lshlrev_b32_e32 v2, 12, v86
	v_lshl_add_u64 v[86:87], v[80:81], 0, v[2:3]
	v_lshlrev_b32_e32 v2, 12, v25
	v_lshl_add_u64 v[80:81], v[80:81], 0, v[2:3]
	s_waitcnt lgkmcnt(0)
	ds_read_b32 v22, v69
	ds_read_b32 v23, v69 offset:132
	ds_read_b32 v24, v69 offset:264
	ds_read_b32 v25, v69 offset:396
	ds_read_b32 v79, v69 offset:528
	ds_read_b32 v88, v69 offset:660
	ds_read_b32 v89, v69 offset:792
	ds_read_b32 v90, v69 offset:924
	s_waitcnt lgkmcnt(7)
	v_bfe_u32 v91, v22, 16, 1
	s_waitcnt lgkmcnt(5)
	v_bfe_u32 v93, v24, 16, 1
	s_waitcnt lgkmcnt(3)
	v_bfe_u32 v95, v79, 16, 1
	s_waitcnt lgkmcnt(1)
	v_bfe_u32 v97, v89, 16, 1
	v_bfe_u32 v92, v23, 16, 1
	v_bfe_u32 v94, v25, 16, 1
	v_bfe_u32 v96, v88, 16, 1
	s_waitcnt lgkmcnt(0)
	v_bfe_u32 v98, v90, 16, 1
	v_add3_u32 v22, v22, v91, s56
	v_add3_u32 v24, v24, v93, s56
	v_add3_u32 v79, v79, v95, s56
	v_add3_u32 v89, v89, v97, s56
	v_add3_u32 v23, v23, v92, s56
	v_add3_u32 v25, v25, v94, s56
	v_add3_u32 v88, v88, v96, s56
	v_add3_u32 v90, v90, v98, s56
	v_lshrrev_b32_e32 v22, 16, v22
	v_lshrrev_b32_e32 v24, 16, v24
	v_lshrrev_b32_e32 v79, 16, v79
	v_lshrrev_b32_e32 v89, 16, v89
	v_and_or_b32 v22, v23, s57, v22
	v_and_or_b32 v23, v25, s57, v24
	v_and_or_b32 v24, v88, s57, v79
	v_and_or_b32 v25, v90, s57, v89
	flat_store_dwordx4 v[82:83], v[22:25]
	ds_read_b32 v22, v69 offset:32
	ds_read_b32 v23, v69 offset:164
	ds_read_b32 v24, v69 offset:296
	ds_read_b32 v25, v69 offset:428
	ds_read_b32 v79, v69 offset:560
	ds_read_b32 v82, v69 offset:692
	ds_read_b32 v83, v69 offset:824
	ds_read_b32 v88, v69 offset:956
	s_waitcnt lgkmcnt(0)
	v_bfe_u32 v89, v22, 16, 1
	v_bfe_u32 v91, v24, 16, 1
	v_bfe_u32 v93, v79, 16, 1
	v_bfe_u32 v95, v83, 16, 1
	v_bfe_u32 v90, v23, 16, 1
	v_bfe_u32 v92, v25, 16, 1
	v_bfe_u32 v94, v82, 16, 1
	v_bfe_u32 v96, v88, 16, 1
	v_add3_u32 v22, v22, v89, s56
	v_add3_u32 v24, v24, v91, s56
	v_add3_u32 v79, v79, v93, s56
	v_add3_u32 v83, v83, v95, s56
	v_add3_u32 v23, v23, v90, s56
	v_add3_u32 v25, v25, v92, s56
	v_add3_u32 v82, v82, v94, s56
	v_add3_u32 v88, v88, v96, s56
	v_lshrrev_b32_e32 v22, 16, v22
	v_lshrrev_b32_e32 v24, 16, v24
	v_lshrrev_b32_e32 v79, 16, v79
	v_lshrrev_b32_e32 v83, 16, v83
	v_and_or_b32 v22, v23, s57, v22
	v_and_or_b32 v23, v25, s57, v24
	v_and_or_b32 v24, v82, s57, v79
	v_and_or_b32 v25, v88, s57, v83
	flat_store_dwordx4 v[84:85], v[22:25]
	ds_read_b32 v22, v69 offset:64
	ds_read_b32 v23, v69 offset:196
	ds_read_b32 v24, v69 offset:328
	ds_read_b32 v25, v69 offset:460
	ds_read_b32 v79, v69 offset:592
	ds_read_b32 v82, v69 offset:724
	ds_read_b32 v83, v69 offset:856
	ds_read_b32 v84, v69 offset:988
	s_waitcnt lgkmcnt(0)
	v_bfe_u32 v85, v22, 16, 1
	v_bfe_u32 v89, v24, 16, 1
	v_bfe_u32 v91, v79, 16, 1
	v_bfe_u32 v93, v83, 16, 1
	v_bfe_u32 v88, v23, 16, 1
	v_bfe_u32 v90, v25, 16, 1
	v_bfe_u32 v92, v82, 16, 1
	v_bfe_u32 v94, v84, 16, 1
	v_add3_u32 v22, v22, v85, s56
	v_add3_u32 v24, v24, v89, s56
	v_add3_u32 v79, v79, v91, s56
	v_add3_u32 v83, v83, v93, s56
	v_add3_u32 v23, v23, v88, s56
	v_add3_u32 v25, v25, v90, s56
	v_add3_u32 v82, v82, v92, s56
	v_add3_u32 v84, v84, v94, s56
	v_lshrrev_b32_e32 v22, 16, v22
	v_lshrrev_b32_e32 v24, 16, v24
	v_lshrrev_b32_e32 v79, 16, v79
	v_lshrrev_b32_e32 v83, 16, v83
	v_and_or_b32 v22, v23, s57, v22
	v_and_or_b32 v23, v25, s57, v24
	v_and_or_b32 v24, v82, s57, v79
	v_and_or_b32 v25, v84, s57, v83
	flat_store_dwordx4 v[86:87], v[22:25]
	ds_read_b32 v22, v69 offset:96
	ds_read_b32 v23, v69 offset:228
	ds_read_b32 v24, v69 offset:360
	ds_read_b32 v25, v69 offset:492
	ds_read_b32 v79, v69 offset:624
	ds_read_b32 v82, v69 offset:756
	ds_read_b32 v83, v69 offset:888
	ds_read_b32 v84, v69 offset:1020
	s_waitcnt lgkmcnt(0)
	v_bfe_u32 v85, v22, 16, 1
	v_bfe_u32 v87, v24, 16, 1
	v_bfe_u32 v89, v79, 16, 1
	v_bfe_u32 v91, v83, 16, 1
	v_bfe_u32 v86, v23, 16, 1
	v_bfe_u32 v88, v25, 16, 1
	v_bfe_u32 v90, v82, 16, 1
	v_bfe_u32 v92, v84, 16, 1
	v_add3_u32 v22, v22, v85, s56
	v_add3_u32 v24, v24, v87, s56
	v_add3_u32 v79, v79, v89, s56
	v_add3_u32 v83, v83, v91, s56
	v_add3_u32 v23, v23, v86, s56
	v_add3_u32 v25, v25, v88, s56
	v_add3_u32 v82, v82, v90, s56
	v_add3_u32 v84, v84, v92, s56
	v_lshrrev_b32_e32 v22, 16, v22
	v_lshrrev_b32_e32 v24, 16, v24
	v_lshrrev_b32_e32 v79, 16, v79
	v_lshrrev_b32_e32 v83, 16, v83
	v_and_or_b32 v22, v23, s57, v22
	v_and_or_b32 v23, v25, s57, v24
	v_and_or_b32 v24, v82, s57, v79
	v_and_or_b32 v25, v84, s57, v83
	flat_store_dwordx4 v[80:81], v[22:25]
	s_waitcnt lgkmcnt(0)
.LBB0_17:
	s_andn2_saveexec_b64 s[46:47], s[46:47]
	s_cbranch_execz .LBB0_19
	v_add_u32_e32 v2, 0xd400, v78
	v_and_b32_e32 v25, 0x7e0, v74
	v_and_b32_e32 v24, 0xffc0, v2
	v_or_b32_e32 v2, v25, v26
	v_or_b32_e32 v22, v24, v19
	v_lshlrev_b32_e32 v79, 2, v2
	v_lshl_or_b32 v2, v22, 13, v79
	v_lshl_add_u64 v[22:23], s[12:13], 0, v[2:3]
	global_load_dword v126, v[22:23], off
	v_or_b32_e32 v2, v24, v29
	v_lshl_or_b32 v2, v2, 13, v79
	v_lshl_add_u64 v[22:23], s[12:13], 0, v[2:3]
	v_or_b32_e32 v2, v24, v30
	v_lshl_or_b32 v2, v2, 13, v79
	v_or_b32_e32 v86, v25, v71
	global_load_dword v128, v[22:23], off
	v_lshl_add_u64 v[22:23], s[12:13], 0, v[2:3]
	v_or_b32_e32 v2, v24, v31
	v_lshl_or_b32 v2, v2, 13, v79
	global_load_dword v129, v[22:23], off
	v_lshl_add_u64 v[22:23], s[12:13], 0, v[2:3]
	v_or_b32_e32 v2, v24, v32
	v_lshl_or_b32 v2, v2, 13, v79
	global_load_dword v130, v[22:23], off
	v_lshl_add_u64 v[22:23], s[12:13], 0, v[2:3]
	v_or_b32_e32 v2, v24, v33
	v_lshl_or_b32 v2, v2, 13, v79
	global_load_dword v131, v[22:23], off
	v_lshl_add_u64 v[22:23], s[12:13], 0, v[2:3]
	v_or_b32_e32 v2, v24, v34
	v_lshl_or_b32 v2, v2, 13, v79
	global_load_dword v132, v[22:23], off
	v_lshl_add_u64 v[22:23], s[12:13], 0, v[2:3]
	v_or_b32_e32 v2, v24, v36
	v_lshl_or_b32 v2, v2, 13, v79
	global_load_dword v133, v[22:23], off
	v_lshl_add_u64 v[22:23], s[12:13], 0, v[2:3]
	v_or_b32_e32 v2, v24, v37
	v_lshl_or_b32 v2, v2, 13, v79
	global_load_dword v135, v[22:23], off
	v_lshl_add_u64 v[22:23], s[12:13], 0, v[2:3]
	v_or_b32_e32 v2, v24, v38
	v_lshl_or_b32 v2, v2, 13, v79
	global_load_dword v136, v[22:23], off
	v_lshl_add_u64 v[22:23], s[12:13], 0, v[2:3]
	v_or_b32_e32 v2, v24, v39
	v_lshl_or_b32 v2, v2, 13, v79
	global_load_dword v137, v[22:23], off
	v_lshl_add_u64 v[22:23], s[12:13], 0, v[2:3]
	v_or_b32_e32 v2, v24, v40
	v_lshl_or_b32 v2, v2, 13, v79
	global_load_dword v138, v[22:23], off
	v_lshl_add_u64 v[22:23], s[12:13], 0, v[2:3]
	v_or_b32_e32 v2, v24, v41
	v_lshl_or_b32 v2, v2, 13, v79
	global_load_dword v139, v[22:23], off
	v_lshl_add_u64 v[22:23], s[12:13], 0, v[2:3]
	v_or_b32_e32 v2, v24, v43
	v_lshl_or_b32 v2, v2, 13, v79
	global_load_dword v140, v[22:23], off
	v_lshl_add_u64 v[22:23], s[12:13], 0, v[2:3]
	v_or_b32_e32 v2, v24, v46
	v_lshl_or_b32 v2, v2, 13, v79
	global_load_dword v142, v[22:23], off
	v_lshl_add_u64 v[22:23], s[12:13], 0, v[2:3]
	v_or_b32_e32 v2, v24, v48
	v_lshl_or_b32 v2, v2, 13, v79
	global_load_dword v143, v[22:23], off
	v_lshl_add_u64 v[22:23], s[12:13], 0, v[2:3]
	v_or_b32_e32 v2, v24, v49
	v_lshl_or_b32 v2, v2, 13, v79
	global_load_dword v144, v[22:23], off
	v_lshl_add_u64 v[22:23], s[12:13], 0, v[2:3]
	v_or_b32_e32 v2, v24, v50
	v_lshl_or_b32 v2, v2, 13, v79
	global_load_dword v145, v[22:23], off
	v_lshl_add_u64 v[22:23], s[12:13], 0, v[2:3]
	v_or_b32_e32 v2, v24, v52
	v_lshl_or_b32 v2, v2, 13, v79
	global_load_dword v146, v[22:23], off
	v_lshl_add_u64 v[22:23], s[12:13], 0, v[2:3]
	v_or_b32_e32 v2, v24, v54
	v_lshl_or_b32 v2, v2, 13, v79
	global_load_dword v147, v[22:23], off
	v_lshl_add_u64 v[22:23], s[12:13], 0, v[2:3]
	v_or_b32_e32 v2, v24, v55
	v_lshl_or_b32 v2, v2, 13, v79
	global_load_dword v149, v[22:23], off
	v_lshl_add_u64 v[22:23], s[12:13], 0, v[2:3]
	v_or_b32_e32 v2, v24, v56
	v_lshl_or_b32 v2, v2, 13, v79
	global_load_dword v150, v[22:23], off
	v_lshl_add_u64 v[22:23], s[12:13], 0, v[2:3]
	v_or_b32_e32 v2, v24, v57
	v_lshl_or_b32 v2, v2, 13, v79
	global_load_dword v151, v[22:23], off
	v_lshl_add_u64 v[22:23], s[12:13], 0, v[2:3]
	v_or_b32_e32 v2, v24, v58
	v_lshl_or_b32 v2, v2, 13, v79
	global_load_dword v152, v[22:23], off
	v_lshl_add_u64 v[22:23], s[12:13], 0, v[2:3]
	v_or_b32_e32 v2, v24, v59
	v_lshl_or_b32 v2, v2, 13, v79
	global_load_dword v153, v[22:23], off
	v_lshl_add_u64 v[22:23], s[12:13], 0, v[2:3]
	v_or_b32_e32 v2, v24, v61
	v_lshl_or_b32 v2, v2, 13, v79
	global_load_dword v154, v[22:23], off
	v_lshl_add_u64 v[22:23], s[12:13], 0, v[2:3]
	v_or_b32_e32 v2, v24, v62
	v_lshl_or_b32 v2, v2, 13, v79
	global_load_dword v156, v[22:23], off
	v_lshl_add_u64 v[22:23], s[12:13], 0, v[2:3]
	v_or_b32_e32 v2, v24, v63
	v_lshl_or_b32 v2, v2, 13, v79
	global_load_dword v157, v[22:23], off
	v_lshl_add_u64 v[22:23], s[12:13], 0, v[2:3]
	v_or_b32_e32 v2, v24, v64
	v_lshl_or_b32 v2, v2, 13, v79
	global_load_dword v158, v[22:23], off
	v_lshl_add_u64 v[22:23], s[12:13], 0, v[2:3]
	v_or_b32_e32 v2, v24, v65
	v_lshl_or_b32 v2, v2, 13, v79
	global_load_dword v159, v[22:23], off
	v_lshl_add_u64 v[22:23], s[12:13], 0, v[2:3]
	v_or_b32_e32 v2, v24, v66
	v_lshl_or_b32 v2, v2, 13, v79
	global_load_dword v160, v[22:23], off
	v_lshl_add_u64 v[22:23], s[12:13], 0, v[2:3]
	v_or_b32_e32 v2, v24, v67
	v_lshl_or_b32 v2, v2, 13, v79
	v_or_b32_e32 v79, v25, v70
	global_load_dword v161, v[22:23], off
	v_lshl_add_u64 v[22:23], s[12:13], 0, v[2:3]
	v_lshlrev_b32_e32 v2, 1, v24
	global_load_dword v162, v[22:23], off
	s_waitcnt vmcnt(0) lgkmcnt(0)
	v_add_u32_e32 v127, v27, v28
	v_add_u32_e32 v155, v27, v60
	ds_write_b32 v127, v126
	ds_write_b32 v127, v128 offset:264
	ds_write_b32 v127, v129 offset:528
	ds_write_b32 v127, v130 offset:792
	ds_write_b32 v127, v131 offset:1056
	ds_write_b32 v127, v132 offset:1320
	v_add_u32_e32 v134, v27, v35
	ds_write_b32 v134, v133
	ds_write_b32 v134, v135 offset:264
	ds_write_b32 v134, v136 offset:528
	ds_write_b32 v134, v137 offset:792
	ds_write_b32 v134, v138 offset:1056
	ds_write_b32 v134, v139 offset:1320
	v_add_u32_e32 v141, v27, v42
	ds_write_b32 v141, v140
	ds_write_b32 v141, v142 offset:264
	ds_write_b32 v141, v143 offset:528
	ds_write_b32 v141, v144 offset:792
	ds_write_b32 v141, v145 offset:1056
	ds_write_b32 v141, v146 offset:1320
	v_add_u32_e32 v148, v27, v53
	ds_write_b32 v148, v147
	ds_write_b32 v148, v149 offset:264
	ds_write_b32 v148, v150 offset:528
	ds_write_b32 v148, v151 offset:792
	ds_write_b32 v148, v152 offset:1056
	ds_write_b32 v148, v153 offset:1320
	ds_write_b32 v155, v154
	ds_write_b32 v155, v156 offset:264
	ds_write_b32 v155, v157 offset:528
	ds_write_b32 v155, v158 offset:792
	ds_write_b32 v155, v159 offset:1056
	ds_write_b32 v155, v160 offset:1320
	ds_write_b32 v155, v161 offset:1584
	ds_write_b32 v155, v162 offset:1848
	v_or_b32_e32 v23, v25, v68
	v_lshl_add_u64 v[80:81], v[10:11], 0, v[2:3]
	v_lshlrev_b32_e32 v2, 12, v23
	v_lshl_add_u64 v[82:83], v[80:81], 0, v[2:3]
	v_lshlrev_b32_e32 v2, 12, v79
	v_or_b32_e32 v25, v25, v72
	v_lshl_add_u64 v[84:85], v[80:81], 0, v[2:3]
	v_lshlrev_b32_e32 v2, 12, v86
	v_lshl_add_u64 v[86:87], v[80:81], 0, v[2:3]
	v_lshlrev_b32_e32 v2, 12, v25
	v_lshl_add_u64 v[80:81], v[80:81], 0, v[2:3]
	s_waitcnt lgkmcnt(0)
	ds_read_b32 v22, v69
	ds_read_b32 v23, v69 offset:132
	ds_read_b32 v24, v69 offset:264
	ds_read_b32 v25, v69 offset:396
	ds_read_b32 v79, v69 offset:528
	ds_read_b32 v88, v69 offset:660
	ds_read_b32 v89, v69 offset:792
	ds_read_b32 v90, v69 offset:924
	s_waitcnt lgkmcnt(7)
	v_bfe_u32 v91, v22, 16, 1
	s_waitcnt lgkmcnt(5)
	v_bfe_u32 v93, v24, 16, 1
	s_waitcnt lgkmcnt(3)
	v_bfe_u32 v95, v79, 16, 1
	s_waitcnt lgkmcnt(1)
	v_bfe_u32 v97, v89, 16, 1
	v_bfe_u32 v92, v23, 16, 1
	v_bfe_u32 v94, v25, 16, 1
	v_bfe_u32 v96, v88, 16, 1
	s_waitcnt lgkmcnt(0)
	v_bfe_u32 v98, v90, 16, 1
	v_add3_u32 v22, v22, v91, s56
	v_add3_u32 v24, v24, v93, s56
	v_add3_u32 v79, v79, v95, s56
	v_add3_u32 v89, v89, v97, s56
	v_add3_u32 v23, v23, v92, s56
	v_add3_u32 v25, v25, v94, s56
	v_add3_u32 v88, v88, v96, s56
	v_add3_u32 v90, v90, v98, s56
	v_lshrrev_b32_e32 v22, 16, v22
	v_lshrrev_b32_e32 v24, 16, v24
	v_lshrrev_b32_e32 v79, 16, v79
	v_lshrrev_b32_e32 v89, 16, v89
	v_and_or_b32 v22, v23, s57, v22
	v_and_or_b32 v23, v25, s57, v24
	v_and_or_b32 v24, v88, s57, v79
	v_and_or_b32 v25, v90, s57, v89
	flat_store_dwordx4 v[82:83], v[22:25]
	ds_read_b32 v22, v69 offset:32
	ds_read_b32 v23, v69 offset:164
	ds_read_b32 v24, v69 offset:296
	ds_read_b32 v25, v69 offset:428
	ds_read_b32 v79, v69 offset:560
	ds_read_b32 v82, v69 offset:692
	ds_read_b32 v83, v69 offset:824
	ds_read_b32 v88, v69 offset:956
	s_waitcnt lgkmcnt(0)
	v_bfe_u32 v89, v22, 16, 1
	v_bfe_u32 v91, v24, 16, 1
	v_bfe_u32 v93, v79, 16, 1
	v_bfe_u32 v95, v83, 16, 1
	v_bfe_u32 v90, v23, 16, 1
	v_bfe_u32 v92, v25, 16, 1
	v_bfe_u32 v94, v82, 16, 1
	v_bfe_u32 v96, v88, 16, 1
	v_add3_u32 v22, v22, v89, s56
	v_add3_u32 v24, v24, v91, s56
	v_add3_u32 v79, v79, v93, s56
	v_add3_u32 v83, v83, v95, s56
	v_add3_u32 v23, v23, v90, s56
	v_add3_u32 v25, v25, v92, s56
	v_add3_u32 v82, v82, v94, s56
	v_add3_u32 v88, v88, v96, s56
	v_lshrrev_b32_e32 v22, 16, v22
	v_lshrrev_b32_e32 v24, 16, v24
	v_lshrrev_b32_e32 v79, 16, v79
	v_lshrrev_b32_e32 v83, 16, v83
	v_and_or_b32 v22, v23, s57, v22
	v_and_or_b32 v23, v25, s57, v24
	v_and_or_b32 v24, v82, s57, v79
	v_and_or_b32 v25, v88, s57, v83
	flat_store_dwordx4 v[84:85], v[22:25]
	ds_read_b32 v22, v69 offset:64
	ds_read_b32 v23, v69 offset:196
	ds_read_b32 v24, v69 offset:328
	ds_read_b32 v25, v69 offset:460
	ds_read_b32 v79, v69 offset:592
	ds_read_b32 v82, v69 offset:724
	ds_read_b32 v83, v69 offset:856
	ds_read_b32 v84, v69 offset:988
	s_waitcnt lgkmcnt(0)
	v_bfe_u32 v85, v22, 16, 1
	v_bfe_u32 v89, v24, 16, 1
	v_bfe_u32 v91, v79, 16, 1
	v_bfe_u32 v93, v83, 16, 1
	v_bfe_u32 v88, v23, 16, 1
	v_bfe_u32 v90, v25, 16, 1
	v_bfe_u32 v92, v82, 16, 1
	v_bfe_u32 v94, v84, 16, 1
	v_add3_u32 v22, v22, v85, s56
	v_add3_u32 v24, v24, v89, s56
	v_add3_u32 v79, v79, v91, s56
	v_add3_u32 v83, v83, v93, s56
	v_add3_u32 v23, v23, v88, s56
	v_add3_u32 v25, v25, v90, s56
	v_add3_u32 v82, v82, v92, s56
	v_add3_u32 v84, v84, v94, s56
	v_lshrrev_b32_e32 v22, 16, v22
	v_lshrrev_b32_e32 v24, 16, v24
	v_lshrrev_b32_e32 v79, 16, v79
	v_lshrrev_b32_e32 v83, 16, v83
	v_and_or_b32 v22, v23, s57, v22
	v_and_or_b32 v23, v25, s57, v24
	v_and_or_b32 v24, v82, s57, v79
	v_and_or_b32 v25, v84, s57, v83
	flat_store_dwordx4 v[86:87], v[22:25]
	ds_read_b32 v22, v69 offset:96
	ds_read_b32 v23, v69 offset:228
	ds_read_b32 v24, v69 offset:360
	ds_read_b32 v25, v69 offset:492
	ds_read_b32 v79, v69 offset:624
	ds_read_b32 v82, v69 offset:756
	ds_read_b32 v83, v69 offset:888
	ds_read_b32 v84, v69 offset:1020
	s_waitcnt lgkmcnt(0)
	v_bfe_u32 v85, v22, 16, 1
	v_bfe_u32 v87, v24, 16, 1
	v_bfe_u32 v89, v79, 16, 1
	v_bfe_u32 v91, v83, 16, 1
	v_bfe_u32 v86, v23, 16, 1
	v_bfe_u32 v88, v25, 16, 1
	v_bfe_u32 v90, v82, 16, 1
	v_bfe_u32 v92, v84, 16, 1
	v_add3_u32 v22, v22, v85, s56
	v_add3_u32 v24, v24, v87, s56
	v_add3_u32 v79, v79, v89, s56
	v_add3_u32 v83, v83, v91, s56
	v_add3_u32 v23, v23, v86, s56
	v_add3_u32 v25, v25, v88, s56
	v_add3_u32 v82, v82, v90, s56
	v_add3_u32 v84, v84, v92, s56
	v_lshrrev_b32_e32 v22, 16, v22
	v_lshrrev_b32_e32 v24, 16, v24
	v_lshrrev_b32_e32 v79, 16, v79
	v_lshrrev_b32_e32 v83, 16, v83
	v_and_or_b32 v22, v23, s57, v22
	v_and_or_b32 v23, v25, s57, v24
	v_and_or_b32 v24, v82, s57, v79
	v_and_or_b32 v25, v84, s57, v83
	flat_store_dwordx4 v[80:81], v[22:25]
	s_waitcnt lgkmcnt(0)

.LBB0_20:
	s_andn2_saveexec_b64 s[44:45], s[44:45]
	s_cbranch_execz .LBB0_22
	v_add_u32_e32 v2, 0xdc00, v78
	v_and_b32_e32 v25, 0x7e0, v74
	v_and_b32_e32 v24, 0xffc0, v2
	v_or_b32_e32 v2, v25, v26
	v_or_b32_e32 v22, v24, v19
	v_lshlrev_b32_e32 v79, 2, v2
	v_lshl_or_b32 v2, v22, 13, v79
	v_lshl_add_u64 v[22:23], s[10:11], 0, v[2:3]
	global_load_dword v126, v[22:23], off
	v_or_b32_e32 v2, v24, v29
	v_lshl_or_b32 v2, v2, 13, v79
	v_lshl_add_u64 v[22:23], s[10:11], 0, v[2:3]
	v_or_b32_e32 v2, v24, v30
	v_lshl_or_b32 v2, v2, 13, v79
	v_or_b32_e32 v86, v25, v71
	global_load_dword v128, v[22:23], off
	v_lshl_add_u64 v[22:23], s[10:11], 0, v[2:3]
	v_or_b32_e32 v2, v24, v31
	v_lshl_or_b32 v2, v2, 13, v79
	global_load_dword v129, v[22:23], off
	v_lshl_add_u64 v[22:23], s[10:11], 0, v[2:3]
	v_or_b32_e32 v2, v24, v32
	v_lshl_or_b32 v2, v2, 13, v79
	global_load_dword v130, v[22:23], off
	v_lshl_add_u64 v[22:23], s[10:11], 0, v[2:3]
	v_or_b32_e32 v2, v24, v33
	v_lshl_or_b32 v2, v2, 13, v79
	global_load_dword v131, v[22:23], off
	v_lshl_add_u64 v[22:23], s[10:11], 0, v[2:3]
	v_or_b32_e32 v2, v24, v34
	v_lshl_or_b32 v2, v2, 13, v79
	global_load_dword v132, v[22:23], off
	v_lshl_add_u64 v[22:23], s[10:11], 0, v[2:3]
	v_or_b32_e32 v2, v24, v36
	v_lshl_or_b32 v2, v2, 13, v79
	global_load_dword v133, v[22:23], off
	v_lshl_add_u64 v[22:23], s[10:11], 0, v[2:3]
	v_or_b32_e32 v2, v24, v37
	v_lshl_or_b32 v2, v2, 13, v79
	global_load_dword v135, v[22:23], off
	v_lshl_add_u64 v[22:23], s[10:11], 0, v[2:3]
	v_or_b32_e32 v2, v24, v38
	v_lshl_or_b32 v2, v2, 13, v79
	global_load_dword v136, v[22:23], off
	v_lshl_add_u64 v[22:23], s[10:11], 0, v[2:3]
	v_or_b32_e32 v2, v24, v39
	v_lshl_or_b32 v2, v2, 13, v79
	global_load_dword v137, v[22:23], off
	v_lshl_add_u64 v[22:23], s[10:11], 0, v[2:3]
	v_or_b32_e32 v2, v24, v40
	v_lshl_or_b32 v2, v2, 13, v79
	global_load_dword v138, v[22:23], off
	v_lshl_add_u64 v[22:23], s[10:11], 0, v[2:3]
	v_or_b32_e32 v2, v24, v41
	v_lshl_or_b32 v2, v2, 13, v79
	global_load_dword v139, v[22:23], off
	v_lshl_add_u64 v[22:23], s[10:11], 0, v[2:3]
	v_or_b32_e32 v2, v24, v43
	v_lshl_or_b32 v2, v2, 13, v79
	global_load_dword v140, v[22:23], off
	v_lshl_add_u64 v[22:23], s[10:11], 0, v[2:3]
	v_or_b32_e32 v2, v24, v46
	v_lshl_or_b32 v2, v2, 13, v79
	global_load_dword v142, v[22:23], off
	v_lshl_add_u64 v[22:23], s[10:11], 0, v[2:3]
	v_or_b32_e32 v2, v24, v48
	v_lshl_or_b32 v2, v2, 13, v79
	global_load_dword v143, v[22:23], off
	v_lshl_add_u64 v[22:23], s[10:11], 0, v[2:3]
	v_or_b32_e32 v2, v24, v49
	v_lshl_or_b32 v2, v2, 13, v79
	global_load_dword v144, v[22:23], off
	v_lshl_add_u64 v[22:23], s[10:11], 0, v[2:3]
	v_or_b32_e32 v2, v24, v50
	v_lshl_or_b32 v2, v2, 13, v79
	global_load_dword v145, v[22:23], off
	v_lshl_add_u64 v[22:23], s[10:11], 0, v[2:3]
	v_or_b32_e32 v2, v24, v52
	v_lshl_or_b32 v2, v2, 13, v79
	global_load_dword v146, v[22:23], off
	v_lshl_add_u64 v[22:23], s[10:11], 0, v[2:3]
	v_or_b32_e32 v2, v24, v54
	v_lshl_or_b32 v2, v2, 13, v79
	global_load_dword v147, v[22:23], off
	v_lshl_add_u64 v[22:23], s[10:11], 0, v[2:3]
	v_or_b32_e32 v2, v24, v55
	v_lshl_or_b32 v2, v2, 13, v79
	global_load_dword v149, v[22:23], off
	v_lshl_add_u64 v[22:23], s[10:11], 0, v[2:3]
	v_or_b32_e32 v2, v24, v56
	v_lshl_or_b32 v2, v2, 13, v79
	global_load_dword v150, v[22:23], off
	v_lshl_add_u64 v[22:23], s[10:11], 0, v[2:3]
	v_or_b32_e32 v2, v24, v57
	v_lshl_or_b32 v2, v2, 13, v79
	global_load_dword v151, v[22:23], off
	v_lshl_add_u64 v[22:23], s[10:11], 0, v[2:3]
	v_or_b32_e32 v2, v24, v58
	v_lshl_or_b32 v2, v2, 13, v79
	global_load_dword v152, v[22:23], off
	v_lshl_add_u64 v[22:23], s[10:11], 0, v[2:3]
	v_or_b32_e32 v2, v24, v59
	v_lshl_or_b32 v2, v2, 13, v79
	global_load_dword v153, v[22:23], off
	v_lshl_add_u64 v[22:23], s[10:11], 0, v[2:3]
	v_or_b32_e32 v2, v24, v61
	v_lshl_or_b32 v2, v2, 13, v79
	global_load_dword v154, v[22:23], off
	v_lshl_add_u64 v[22:23], s[10:11], 0, v[2:3]
	v_or_b32_e32 v2, v24, v62
	v_lshl_or_b32 v2, v2, 13, v79
	global_load_dword v156, v[22:23], off
	v_lshl_add_u64 v[22:23], s[10:11], 0, v[2:3]
	v_or_b32_e32 v2, v24, v63
	v_lshl_or_b32 v2, v2, 13, v79
	global_load_dword v157, v[22:23], off
	v_lshl_add_u64 v[22:23], s[10:11], 0, v[2:3]
	v_or_b32_e32 v2, v24, v64
	v_lshl_or_b32 v2, v2, 13, v79
	global_load_dword v158, v[22:23], off
	v_lshl_add_u64 v[22:23], s[10:11], 0, v[2:3]
	v_or_b32_e32 v2, v24, v65
	v_lshl_or_b32 v2, v2, 13, v79
	global_load_dword v159, v[22:23], off
	v_lshl_add_u64 v[22:23], s[10:11], 0, v[2:3]
	v_or_b32_e32 v2, v24, v66
	v_lshl_or_b32 v2, v2, 13, v79
	global_load_dword v160, v[22:23], off
	v_lshl_add_u64 v[22:23], s[10:11], 0, v[2:3]
	v_or_b32_e32 v2, v24, v67
	v_lshl_or_b32 v2, v2, 13, v79
	v_or_b32_e32 v79, v25, v70
	global_load_dword v161, v[22:23], off
	v_lshl_add_u64 v[22:23], s[10:11], 0, v[2:3]
	v_lshlrev_b32_e32 v2, 1, v24
	global_load_dword v162, v[22:23], off
	s_waitcnt vmcnt(0) lgkmcnt(0)
	v_add_u32_e32 v127, v27, v28
	v_add_u32_e32 v155, v27, v60
	ds_write_b32 v127, v126
	ds_write_b32 v127, v128 offset:264
	ds_write_b32 v127, v129 offset:528
	ds_write_b32 v127, v130 offset:792
	ds_write_b32 v127, v131 offset:1056
	ds_write_b32 v127, v132 offset:1320
	v_add_u32_e32 v134, v27, v35
	ds_write_b32 v134, v133
	ds_write_b32 v134, v135 offset:264
	ds_write_b32 v134, v136 offset:528
	ds_write_b32 v134, v137 offset:792
	ds_write_b32 v134, v138 offset:1056
	ds_write_b32 v134, v139 offset:1320
	v_add_u32_e32 v141, v27, v42
	ds_write_b32 v141, v140
	ds_write_b32 v141, v142 offset:264
	ds_write_b32 v141, v143 offset:528
	ds_write_b32 v141, v144 offset:792
	ds_write_b32 v141, v145 offset:1056
	ds_write_b32 v141, v146 offset:1320
	v_add_u32_e32 v148, v27, v53
	ds_write_b32 v148, v147
	ds_write_b32 v148, v149 offset:264
	ds_write_b32 v148, v150 offset:528
	ds_write_b32 v148, v151 offset:792
	ds_write_b32 v148, v152 offset:1056
	ds_write_b32 v148, v153 offset:1320
	ds_write_b32 v155, v154
	ds_write_b32 v155, v156 offset:264
	ds_write_b32 v155, v157 offset:528
	ds_write_b32 v155, v158 offset:792
	ds_write_b32 v155, v159 offset:1056
	ds_write_b32 v155, v160 offset:1320
	ds_write_b32 v155, v161 offset:1584
	ds_write_b32 v155, v162 offset:1848
	v_or_b32_e32 v23, v25, v68
	v_lshl_add_u64 v[80:81], v[12:13], 0, v[2:3]
	v_lshlrev_b32_e32 v2, 12, v23
	v_lshl_add_u64 v[82:83], v[80:81], 0, v[2:3]
	v_lshlrev_b32_e32 v2, 12, v79
	v_or_b32_e32 v25, v25, v72
	v_lshl_add_u64 v[84:85], v[80:81], 0, v[2:3]
	v_lshlrev_b32_e32 v2, 12, v86
	v_lshl_add_u64 v[86:87], v[80:81], 0, v[2:3]
	v_lshlrev_b32_e32 v2, 12, v25
	v_lshl_add_u64 v[80:81], v[80:81], 0, v[2:3]
	s_waitcnt lgkmcnt(0)
	ds_read_b32 v22, v69
	ds_read_b32 v23, v69 offset:132
	ds_read_b32 v24, v69 offset:264
	ds_read_b32 v25, v69 offset:396
	ds_read_b32 v79, v69 offset:528
	ds_read_b32 v88, v69 offset:660
	ds_read_b32 v89, v69 offset:792
	ds_read_b32 v90, v69 offset:924
	s_waitcnt lgkmcnt(7)
	v_bfe_u32 v91, v22, 16, 1
	s_waitcnt lgkmcnt(5)
	v_bfe_u32 v93, v24, 16, 1
	s_waitcnt lgkmcnt(3)
	v_bfe_u32 v95, v79, 16, 1
	s_waitcnt lgkmcnt(1)
	v_bfe_u32 v97, v89, 16, 1
	v_bfe_u32 v92, v23, 16, 1
	v_bfe_u32 v94, v25, 16, 1
	v_bfe_u32 v96, v88, 16, 1
	s_waitcnt lgkmcnt(0)
	v_bfe_u32 v98, v90, 16, 1
	v_add3_u32 v22, v22, v91, s56
	v_add3_u32 v24, v24, v93, s56
	v_add3_u32 v79, v79, v95, s56
	v_add3_u32 v89, v89, v97, s56
	v_add3_u32 v23, v23, v92, s56
	v_add3_u32 v25, v25, v94, s56
	v_add3_u32 v88, v88, v96, s56
	v_add3_u32 v90, v90, v98, s56
	v_lshrrev_b32_e32 v22, 16, v22
	v_lshrrev_b32_e32 v24, 16, v24
	v_lshrrev_b32_e32 v79, 16, v79
	v_lshrrev_b32_e32 v89, 16, v89
	v_and_or_b32 v22, v23, s57, v22
	v_and_or_b32 v23, v25, s57, v24
	v_and_or_b32 v24, v88, s57, v79
	v_and_or_b32 v25, v90, s57, v89
	flat_store_dwordx4 v[82:83], v[22:25]
	ds_read_b32 v22, v69 offset:32
	ds_read_b32 v23, v69 offset:164
	ds_read_b32 v24, v69 offset:296
	ds_read_b32 v25, v69 offset:428
	ds_read_b32 v79, v69 offset:560
	ds_read_b32 v82, v69 offset:692
	ds_read_b32 v83, v69 offset:824
	ds_read_b32 v88, v69 offset:956
	s_waitcnt lgkmcnt(0)
	v_bfe_u32 v89, v22, 16, 1
	v_bfe_u32 v91, v24, 16, 1
	v_bfe_u32 v93, v79, 16, 1
	v_bfe_u32 v95, v83, 16, 1
	v_bfe_u32 v90, v23, 16, 1
	v_bfe_u32 v92, v25, 16, 1
	v_bfe_u32 v94, v82, 16, 1
	v_bfe_u32 v96, v88, 16, 1
	v_add3_u32 v22, v22, v89, s56
	v_add3_u32 v24, v24, v91, s56
	v_add3_u32 v79, v79, v93, s56
	v_add3_u32 v83, v83, v95, s56
	v_add3_u32 v23, v23, v90, s56
	v_add3_u32 v25, v25, v92, s56
	v_add3_u32 v82, v82, v94, s56
	v_add3_u32 v88, v88, v96, s56
	v_lshrrev_b32_e32 v22, 16, v22
	v_lshrrev_b32_e32 v24, 16, v24
	v_lshrrev_b32_e32 v79, 16, v79
	v_lshrrev_b32_e32 v83, 16, v83
	v_and_or_b32 v22, v23, s57, v22
	v_and_or_b32 v23, v25, s57, v24
	v_and_or_b32 v24, v82, s57, v79
	v_and_or_b32 v25, v88, s57, v83
	flat_store_dwordx4 v[84:85], v[22:25]
	ds_read_b32 v22, v69 offset:64
	ds_read_b32 v23, v69 offset:196
	ds_read_b32 v24, v69 offset:328
	ds_read_b32 v25, v69 offset:460
	ds_read_b32 v79, v69 offset:592
	ds_read_b32 v82, v69 offset:724
	ds_read_b32 v83, v69 offset:856
	ds_read_b32 v84, v69 offset:988
	s_waitcnt lgkmcnt(0)
	v_bfe_u32 v85, v22, 16, 1
	v_bfe_u32 v89, v24, 16, 1
	v_bfe_u32 v91, v79, 16, 1
	v_bfe_u32 v93, v83, 16, 1
	v_bfe_u32 v88, v23, 16, 1
	v_bfe_u32 v90, v25, 16, 1
	v_bfe_u32 v92, v82, 16, 1
	v_bfe_u32 v94, v84, 16, 1
	v_add3_u32 v22, v22, v85, s56
	v_add3_u32 v24, v24, v89, s56
	v_add3_u32 v79, v79, v91, s56
	v_add3_u32 v83, v83, v93, s56
	v_add3_u32 v23, v23, v88, s56
	v_add3_u32 v25, v25, v90, s56
	v_add3_u32 v82, v82, v92, s56
	v_add3_u32 v84, v84, v94, s56
	v_lshrrev_b32_e32 v22, 16, v22
	v_lshrrev_b32_e32 v24, 16, v24
	v_lshrrev_b32_e32 v79, 16, v79
	v_lshrrev_b32_e32 v83, 16, v83
	v_and_or_b32 v22, v23, s57, v22
	v_and_or_b32 v23, v25, s57, v24
	v_and_or_b32 v24, v82, s57, v79
	v_and_or_b32 v25, v84, s57, v83
	flat_store_dwordx4 v[86:87], v[22:25]
	ds_read_b32 v22, v69 offset:96
	ds_read_b32 v23, v69 offset:228
	ds_read_b32 v24, v69 offset:360
	ds_read_b32 v25, v69 offset:492
	ds_read_b32 v79, v69 offset:624
	ds_read_b32 v82, v69 offset:756
	ds_read_b32 v83, v69 offset:888
	ds_read_b32 v84, v69 offset:1020
	s_waitcnt lgkmcnt(0)
	v_bfe_u32 v85, v22, 16, 1
	v_bfe_u32 v87, v24, 16, 1
	v_bfe_u32 v89, v79, 16, 1
	v_bfe_u32 v91, v83, 16, 1
	v_bfe_u32 v86, v23, 16, 1
	v_bfe_u32 v88, v25, 16, 1
	v_bfe_u32 v90, v82, 16, 1
	v_bfe_u32 v92, v84, 16, 1
	v_add3_u32 v22, v22, v85, s56
	v_add3_u32 v24, v24, v87, s56
	v_add3_u32 v79, v79, v89, s56
	v_add3_u32 v83, v83, v91, s56
	v_add3_u32 v23, v23, v86, s56
	v_add3_u32 v25, v25, v88, s56
	v_add3_u32 v82, v82, v90, s56
	v_add3_u32 v84, v84, v92, s56
	v_lshrrev_b32_e32 v22, 16, v22
	v_lshrrev_b32_e32 v24, 16, v24
	v_lshrrev_b32_e32 v79, 16, v79
	v_lshrrev_b32_e32 v83, 16, v83
	v_and_or_b32 v22, v23, s57, v22
	v_and_or_b32 v23, v25, s57, v24
	v_and_or_b32 v24, v82, s57, v79
	v_and_or_b32 v25, v84, s57, v83
	flat_store_dwordx4 v[80:81], v[22:25]
	s_waitcnt lgkmcnt(0)

.LBB0_23:
	s_andn2_saveexec_b64 s[42:43], s[42:43]
	s_cbranch_execz .LBB0_25
	v_add_u32_e32 v2, 0xe400, v78
	v_and_b32_e32 v25, 0x7e0, v74
	v_and_b32_e32 v24, 0xffc0, v2
	v_or_b32_e32 v2, v25, v26
	v_or_b32_e32 v22, v24, v19
	v_lshlrev_b32_e32 v79, 2, v2
	v_lshl_or_b32 v2, v22, 13, v79
	v_lshl_add_u64 v[22:23], s[8:9], 0, v[2:3]
	global_load_dword v126, v[22:23], off
	v_or_b32_e32 v2, v24, v29
	v_lshl_or_b32 v2, v2, 13, v79
	v_lshl_add_u64 v[22:23], s[8:9], 0, v[2:3]
	v_or_b32_e32 v2, v24, v30
	v_lshl_or_b32 v2, v2, 13, v79
	v_or_b32_e32 v86, v25, v71
	global_load_dword v128, v[22:23], off
	v_lshl_add_u64 v[22:23], s[8:9], 0, v[2:3]
	v_or_b32_e32 v2, v24, v31
	v_lshl_or_b32 v2, v2, 13, v79
	global_load_dword v129, v[22:23], off
	v_lshl_add_u64 v[22:23], s[8:9], 0, v[2:3]
	v_or_b32_e32 v2, v24, v32
	v_lshl_or_b32 v2, v2, 13, v79
	global_load_dword v130, v[22:23], off
	v_lshl_add_u64 v[22:23], s[8:9], 0, v[2:3]
	v_or_b32_e32 v2, v24, v33
	v_lshl_or_b32 v2, v2, 13, v79
	global_load_dword v131, v[22:23], off
	v_lshl_add_u64 v[22:23], s[8:9], 0, v[2:3]
	v_or_b32_e32 v2, v24, v34
	v_lshl_or_b32 v2, v2, 13, v79
	global_load_dword v132, v[22:23], off
	v_lshl_add_u64 v[22:23], s[8:9], 0, v[2:3]
	v_or_b32_e32 v2, v24, v36
	v_lshl_or_b32 v2, v2, 13, v79
	global_load_dword v133, v[22:23], off
	v_lshl_add_u64 v[22:23], s[8:9], 0, v[2:3]
	v_or_b32_e32 v2, v24, v37
	v_lshl_or_b32 v2, v2, 13, v79
	global_load_dword v135, v[22:23], off
	v_lshl_add_u64 v[22:23], s[8:9], 0, v[2:3]
	v_or_b32_e32 v2, v24, v38
	v_lshl_or_b32 v2, v2, 13, v79
	global_load_dword v136, v[22:23], off
	v_lshl_add_u64 v[22:23], s[8:9], 0, v[2:3]
	v_or_b32_e32 v2, v24, v39
	v_lshl_or_b32 v2, v2, 13, v79
	global_load_dword v137, v[22:23], off
	v_lshl_add_u64 v[22:23], s[8:9], 0, v[2:3]
	v_or_b32_e32 v2, v24, v40
	v_lshl_or_b32 v2, v2, 13, v79
	global_load_dword v138, v[22:23], off
	v_lshl_add_u64 v[22:23], s[8:9], 0, v[2:3]
	v_or_b32_e32 v2, v24, v41
	v_lshl_or_b32 v2, v2, 13, v79
	global_load_dword v139, v[22:23], off
	v_lshl_add_u64 v[22:23], s[8:9], 0, v[2:3]
	v_or_b32_e32 v2, v24, v43
	v_lshl_or_b32 v2, v2, 13, v79
	global_load_dword v140, v[22:23], off
	v_lshl_add_u64 v[22:23], s[8:9], 0, v[2:3]
	v_or_b32_e32 v2, v24, v46
	v_lshl_or_b32 v2, v2, 13, v79
	global_load_dword v142, v[22:23], off
	v_lshl_add_u64 v[22:23], s[8:9], 0, v[2:3]
	v_or_b32_e32 v2, v24, v48
	v_lshl_or_b32 v2, v2, 13, v79
	global_load_dword v143, v[22:23], off
	v_lshl_add_u64 v[22:23], s[8:9], 0, v[2:3]
	v_or_b32_e32 v2, v24, v49
	v_lshl_or_b32 v2, v2, 13, v79
	global_load_dword v144, v[22:23], off
	v_lshl_add_u64 v[22:23], s[8:9], 0, v[2:3]
	v_or_b32_e32 v2, v24, v50
	v_lshl_or_b32 v2, v2, 13, v79
	global_load_dword v145, v[22:23], off
	v_lshl_add_u64 v[22:23], s[8:9], 0, v[2:3]
	v_or_b32_e32 v2, v24, v52
	v_lshl_or_b32 v2, v2, 13, v79
	global_load_dword v146, v[22:23], off
	v_lshl_add_u64 v[22:23], s[8:9], 0, v[2:3]
	v_or_b32_e32 v2, v24, v54
	v_lshl_or_b32 v2, v2, 13, v79
	global_load_dword v147, v[22:23], off
	v_lshl_add_u64 v[22:23], s[8:9], 0, v[2:3]
	v_or_b32_e32 v2, v24, v55
	v_lshl_or_b32 v2, v2, 13, v79
	global_load_dword v149, v[22:23], off
	v_lshl_add_u64 v[22:23], s[8:9], 0, v[2:3]
	v_or_b32_e32 v2, v24, v56
	v_lshl_or_b32 v2, v2, 13, v79
	global_load_dword v150, v[22:23], off
	v_lshl_add_u64 v[22:23], s[8:9], 0, v[2:3]
	v_or_b32_e32 v2, v24, v57
	v_lshl_or_b32 v2, v2, 13, v79
	global_load_dword v151, v[22:23], off
	v_lshl_add_u64 v[22:23], s[8:9], 0, v[2:3]
	v_or_b32_e32 v2, v24, v58
	v_lshl_or_b32 v2, v2, 13, v79
	global_load_dword v152, v[22:23], off
	v_lshl_add_u64 v[22:23], s[8:9], 0, v[2:3]
	v_or_b32_e32 v2, v24, v59
	v_lshl_or_b32 v2, v2, 13, v79
	global_load_dword v153, v[22:23], off
	v_lshl_add_u64 v[22:23], s[8:9], 0, v[2:3]
	v_or_b32_e32 v2, v24, v61
	v_lshl_or_b32 v2, v2, 13, v79
	global_load_dword v154, v[22:23], off
	v_lshl_add_u64 v[22:23], s[8:9], 0, v[2:3]
	v_or_b32_e32 v2, v24, v62
	v_lshl_or_b32 v2, v2, 13, v79
	global_load_dword v156, v[22:23], off
	v_lshl_add_u64 v[22:23], s[8:9], 0, v[2:3]
	v_or_b32_e32 v2, v24, v63
	v_lshl_or_b32 v2, v2, 13, v79
	global_load_dword v157, v[22:23], off
	v_lshl_add_u64 v[22:23], s[8:9], 0, v[2:3]
	v_or_b32_e32 v2, v24, v64
	v_lshl_or_b32 v2, v2, 13, v79
	global_load_dword v158, v[22:23], off
	v_lshl_add_u64 v[22:23], s[8:9], 0, v[2:3]
	v_or_b32_e32 v2, v24, v65
	v_lshl_or_b32 v2, v2, 13, v79
	global_load_dword v159, v[22:23], off
	v_lshl_add_u64 v[22:23], s[8:9], 0, v[2:3]
	v_or_b32_e32 v2, v24, v66
	v_lshl_or_b32 v2, v2, 13, v79
	global_load_dword v160, v[22:23], off
	v_lshl_add_u64 v[22:23], s[8:9], 0, v[2:3]
	v_or_b32_e32 v2, v24, v67
	v_lshl_or_b32 v2, v2, 13, v79
	v_or_b32_e32 v79, v25, v70
	global_load_dword v161, v[22:23], off
	v_lshl_add_u64 v[22:23], s[8:9], 0, v[2:3]
	v_lshlrev_b32_e32 v2, 1, v24
	global_load_dword v162, v[22:23], off
	s_waitcnt vmcnt(0) lgkmcnt(0)
	v_add_u32_e32 v127, v27, v28
	v_add_u32_e32 v155, v27, v60
	ds_write_b32 v127, v126
	ds_write_b32 v127, v128 offset:264
	ds_write_b32 v127, v129 offset:528
	ds_write_b32 v127, v130 offset:792
	ds_write_b32 v127, v131 offset:1056
	ds_write_b32 v127, v132 offset:1320
	v_add_u32_e32 v134, v27, v35
	ds_write_b32 v134, v133
	ds_write_b32 v134, v135 offset:264
	ds_write_b32 v134, v136 offset:528
	ds_write_b32 v134, v137 offset:792
	ds_write_b32 v134, v138 offset:1056
	ds_write_b32 v134, v139 offset:1320
	v_add_u32_e32 v141, v27, v42
	ds_write_b32 v141, v140
	ds_write_b32 v141, v142 offset:264
	ds_write_b32 v141, v143 offset:528
	ds_write_b32 v141, v144 offset:792
	ds_write_b32 v141, v145 offset:1056
	ds_write_b32 v141, v146 offset:1320
	v_add_u32_e32 v148, v27, v53
	ds_write_b32 v148, v147
	ds_write_b32 v148, v149 offset:264
	ds_write_b32 v148, v150 offset:528
	ds_write_b32 v148, v151 offset:792
	ds_write_b32 v148, v152 offset:1056
	ds_write_b32 v148, v153 offset:1320
	ds_write_b32 v155, v154
	ds_write_b32 v155, v156 offset:264
	ds_write_b32 v155, v157 offset:528
	ds_write_b32 v155, v158 offset:792
	ds_write_b32 v155, v159 offset:1056
	ds_write_b32 v155, v160 offset:1320
	ds_write_b32 v155, v161 offset:1584
	ds_write_b32 v155, v162 offset:1848
	v_or_b32_e32 v23, v25, v68
	v_lshl_add_u64 v[80:81], v[14:15], 0, v[2:3]
	v_lshlrev_b32_e32 v2, 12, v23
	v_lshl_add_u64 v[82:83], v[80:81], 0, v[2:3]
	v_lshlrev_b32_e32 v2, 12, v79
	v_or_b32_e32 v25, v25, v72
	v_lshl_add_u64 v[84:85], v[80:81], 0, v[2:3]
	v_lshlrev_b32_e32 v2, 12, v86
	v_lshl_add_u64 v[86:87], v[80:81], 0, v[2:3]
	v_lshlrev_b32_e32 v2, 12, v25
	v_lshl_add_u64 v[80:81], v[80:81], 0, v[2:3]
	s_waitcnt lgkmcnt(0)
	ds_read_b32 v22, v69
	ds_read_b32 v23, v69 offset:132
	ds_read_b32 v24, v69 offset:264
	ds_read_b32 v25, v69 offset:396
	ds_read_b32 v79, v69 offset:528
	ds_read_b32 v88, v69 offset:660
	ds_read_b32 v89, v69 offset:792
	ds_read_b32 v90, v69 offset:924
	s_waitcnt lgkmcnt(7)
	v_bfe_u32 v91, v22, 16, 1
	s_waitcnt lgkmcnt(5)
	v_bfe_u32 v93, v24, 16, 1
	s_waitcnt lgkmcnt(3)
	v_bfe_u32 v95, v79, 16, 1
	s_waitcnt lgkmcnt(1)
	v_bfe_u32 v97, v89, 16, 1
	v_bfe_u32 v92, v23, 16, 1
	v_bfe_u32 v94, v25, 16, 1
	v_bfe_u32 v96, v88, 16, 1
	s_waitcnt lgkmcnt(0)
	v_bfe_u32 v98, v90, 16, 1
	v_add3_u32 v22, v22, v91, s56
	v_add3_u32 v24, v24, v93, s56
	v_add3_u32 v79, v79, v95, s56
	v_add3_u32 v89, v89, v97, s56
	v_add3_u32 v23, v23, v92, s56
	v_add3_u32 v25, v25, v94, s56
	v_add3_u32 v88, v88, v96, s56
	v_add3_u32 v90, v90, v98, s56
	v_lshrrev_b32_e32 v22, 16, v22
	v_lshrrev_b32_e32 v24, 16, v24
	v_lshrrev_b32_e32 v79, 16, v79
	v_lshrrev_b32_e32 v89, 16, v89
	v_and_or_b32 v22, v23, s57, v22
	v_and_or_b32 v23, v25, s57, v24
	v_and_or_b32 v24, v88, s57, v79
	v_and_or_b32 v25, v90, s57, v89
	flat_store_dwordx4 v[82:83], v[22:25]
	ds_read_b32 v22, v69 offset:32
	ds_read_b32 v23, v69 offset:164
	ds_read_b32 v24, v69 offset:296
	ds_read_b32 v25, v69 offset:428
	ds_read_b32 v79, v69 offset:560
	ds_read_b32 v82, v69 offset:692
	ds_read_b32 v83, v69 offset:824
	ds_read_b32 v88, v69 offset:956
	s_waitcnt lgkmcnt(0)
	v_bfe_u32 v89, v22, 16, 1
	v_bfe_u32 v91, v24, 16, 1
	v_bfe_u32 v93, v79, 16, 1
	v_bfe_u32 v95, v83, 16, 1
	v_bfe_u32 v90, v23, 16, 1
	v_bfe_u32 v92, v25, 16, 1
	v_bfe_u32 v94, v82, 16, 1
	v_bfe_u32 v96, v88, 16, 1
	v_add3_u32 v22, v22, v89, s56
	v_add3_u32 v24, v24, v91, s56
	v_add3_u32 v79, v79, v93, s56
	v_add3_u32 v83, v83, v95, s56
	v_add3_u32 v23, v23, v90, s56
	v_add3_u32 v25, v25, v92, s56
	v_add3_u32 v82, v82, v94, s56
	v_add3_u32 v88, v88, v96, s56
	v_lshrrev_b32_e32 v22, 16, v22
	v_lshrrev_b32_e32 v24, 16, v24
	v_lshrrev_b32_e32 v79, 16, v79
	v_lshrrev_b32_e32 v83, 16, v83
	v_and_or_b32 v22, v23, s57, v22
	v_and_or_b32 v23, v25, s57, v24
	v_and_or_b32 v24, v82, s57, v79
	v_and_or_b32 v25, v88, s57, v83
	flat_store_dwordx4 v[84:85], v[22:25]
	ds_read_b32 v22, v69 offset:64
	ds_read_b32 v23, v69 offset:196
	ds_read_b32 v24, v69 offset:328
	ds_read_b32 v25, v69 offset:460
	ds_read_b32 v79, v69 offset:592
	ds_read_b32 v82, v69 offset:724
	ds_read_b32 v83, v69 offset:856
	ds_read_b32 v84, v69 offset:988
	s_waitcnt lgkmcnt(0)
	v_bfe_u32 v85, v22, 16, 1
	v_bfe_u32 v89, v24, 16, 1
	v_bfe_u32 v91, v79, 16, 1
	v_bfe_u32 v93, v83, 16, 1
	v_bfe_u32 v88, v23, 16, 1
	v_bfe_u32 v90, v25, 16, 1
	v_bfe_u32 v92, v82, 16, 1
	v_bfe_u32 v94, v84, 16, 1
	v_add3_u32 v22, v22, v85, s56
	v_add3_u32 v24, v24, v89, s56
	v_add3_u32 v79, v79, v91, s56
	v_add3_u32 v83, v83, v93, s56
	v_add3_u32 v23, v23, v88, s56
	v_add3_u32 v25, v25, v90, s56
	v_add3_u32 v82, v82, v92, s56
	v_add3_u32 v84, v84, v94, s56
	v_lshrrev_b32_e32 v22, 16, v22
	v_lshrrev_b32_e32 v24, 16, v24
	v_lshrrev_b32_e32 v79, 16, v79
	v_lshrrev_b32_e32 v83, 16, v83
	v_and_or_b32 v22, v23, s57, v22
	v_and_or_b32 v23, v25, s57, v24
	v_and_or_b32 v24, v82, s57, v79
	v_and_or_b32 v25, v84, s57, v83
	flat_store_dwordx4 v[86:87], v[22:25]
	ds_read_b32 v22, v69 offset:96
	ds_read_b32 v23, v69 offset:228
	ds_read_b32 v24, v69 offset:360
	ds_read_b32 v25, v69 offset:492
	ds_read_b32 v79, v69 offset:624
	ds_read_b32 v82, v69 offset:756
	ds_read_b32 v83, v69 offset:888
	ds_read_b32 v84, v69 offset:1020
	s_waitcnt lgkmcnt(0)
	v_bfe_u32 v85, v22, 16, 1
	v_bfe_u32 v87, v24, 16, 1
	v_bfe_u32 v89, v79, 16, 1
	v_bfe_u32 v91, v83, 16, 1
	v_bfe_u32 v86, v23, 16, 1
	v_bfe_u32 v88, v25, 16, 1
	v_bfe_u32 v90, v82, 16, 1
	v_bfe_u32 v92, v84, 16, 1
	v_add3_u32 v22, v22, v85, s56
	v_add3_u32 v24, v24, v87, s56
	v_add3_u32 v79, v79, v89, s56
	v_add3_u32 v83, v83, v91, s56
	v_add3_u32 v23, v23, v86, s56
	v_add3_u32 v25, v25, v88, s56
	v_add3_u32 v82, v82, v90, s56
	v_add3_u32 v84, v84, v92, s56
	v_lshrrev_b32_e32 v22, 16, v22
	v_lshrrev_b32_e32 v24, 16, v24
	v_lshrrev_b32_e32 v79, 16, v79
	v_lshrrev_b32_e32 v83, 16, v83
	v_and_or_b32 v22, v23, s57, v22
	v_and_or_b32 v23, v25, s57, v24
	v_and_or_b32 v24, v82, s57, v79
	v_and_or_b32 v25, v84, s57, v83
	flat_store_dwordx4 v[80:81], v[22:25]
	s_waitcnt lgkmcnt(0)

.LBB0_26:
	s_andn2_saveexec_b64 s[40:41], s[40:41]
	s_cbranch_execz .LBB0_28
	v_add_u32_e32 v2, 0xec00, v78
	v_lshrrev_b32_e32 v2, 1, v2
	v_and_b32_e32 v23, 0xfe0, v74
	v_and_b32_e32 v22, 0x7fc0, v2
	v_or_b32_e32 v2, v23, v26
	v_or_b32_e32 v79, v22, v19
	v_lshlrev_b32_e32 v82, 2, v2
	v_lshl_or_b32 v2, v79, 14, v82
	v_lshl_add_u64 v[24:25], s[6:7], 0, v[2:3]
	v_lshlrev_b32_e32 v2, 2, v79
	global_load_dword v127, v[24:25], off
	v_lshl_add_u64 v[24:25], s[30:31], 0, v[2:3]
	global_load_dword v128, v[24:25], off
	v_or_b32_e32 v80, v22, v29
	v_lshl_or_b32 v2, v80, 14, v82
	v_lshl_add_u64 v[24:25], s[6:7], 0, v[2:3]
	v_lshlrev_b32_e32 v2, 2, v80
	v_lshl_add_u64 v[80:81], s[30:31], 0, v[2:3]
	v_or_b32_e32 v86, v23, v71
	global_load_dword v131, v[24:25], off
	global_load_dword v132, v[80:81], off
	v_or_b32_e32 v80, v22, v30
	v_lshl_or_b32 v2, v80, 14, v82
	v_lshl_add_u64 v[24:25], s[6:7], 0, v[2:3]
	v_lshlrev_b32_e32 v2, 2, v80
	v_lshl_add_u64 v[80:81], s[30:31], 0, v[2:3]
	global_load_dword v134, v[24:25], off
	global_load_dword v135, v[80:81], off
	v_or_b32_e32 v80, v22, v31
	v_lshl_or_b32 v2, v80, 14, v82
	v_lshl_add_u64 v[24:25], s[6:7], 0, v[2:3]
	v_lshlrev_b32_e32 v2, 2, v80
	v_lshl_add_u64 v[80:81], s[30:31], 0, v[2:3]
	global_load_dword v137, v[24:25], off
	global_load_dword v138, v[80:81], off
	v_or_b32_e32 v80, v22, v32
	v_lshl_or_b32 v2, v80, 14, v82
	v_lshl_add_u64 v[24:25], s[6:7], 0, v[2:3]
	v_lshlrev_b32_e32 v2, 2, v80
	v_lshl_add_u64 v[80:81], s[30:31], 0, v[2:3]
	global_load_dword v140, v[24:25], off
	global_load_dword v141, v[80:81], off
	v_or_b32_e32 v80, v22, v33
	v_lshl_or_b32 v2, v80, 14, v82
	v_lshl_add_u64 v[24:25], s[6:7], 0, v[2:3]
	v_lshlrev_b32_e32 v2, 2, v80
	v_lshl_add_u64 v[80:81], s[30:31], 0, v[2:3]
	global_load_dword v143, v[24:25], off
	global_load_dword v144, v[80:81], off
	v_or_b32_e32 v80, v22, v34
	v_lshl_or_b32 v2, v80, 14, v82
	v_lshl_add_u64 v[24:25], s[6:7], 0, v[2:3]
	v_lshlrev_b32_e32 v2, 2, v80
	v_lshl_add_u64 v[80:81], s[30:31], 0, v[2:3]
	global_load_dword v146, v[24:25], off
	global_load_dword v147, v[80:81], off
	v_or_b32_e32 v80, v22, v36
	v_lshl_or_b32 v2, v80, 14, v82
	v_lshl_add_u64 v[24:25], s[6:7], 0, v[2:3]
	v_lshlrev_b32_e32 v2, 2, v80
	v_lshl_add_u64 v[80:81], s[30:31], 0, v[2:3]
	global_load_dword v150, v[24:25], off
	global_load_dword v151, v[80:81], off
	v_or_b32_e32 v80, v22, v37
	v_lshl_or_b32 v2, v80, 14, v82
	v_lshl_add_u64 v[24:25], s[6:7], 0, v[2:3]
	v_lshlrev_b32_e32 v2, 2, v80
	v_lshl_add_u64 v[80:81], s[30:31], 0, v[2:3]
	global_load_dword v153, v[24:25], off
	global_load_dword v154, v[80:81], off
	v_or_b32_e32 v80, v22, v38
	v_lshl_or_b32 v2, v80, 14, v82
	v_lshl_add_u64 v[24:25], s[6:7], 0, v[2:3]
	v_lshlrev_b32_e32 v2, 2, v80
	v_lshl_add_u64 v[80:81], s[30:31], 0, v[2:3]
	global_load_dword v156, v[24:25], off
	global_load_dword v157, v[80:81], off
	v_or_b32_e32 v80, v22, v39
	v_lshl_or_b32 v2, v80, 14, v82
	v_lshl_add_u64 v[24:25], s[6:7], 0, v[2:3]
	v_lshlrev_b32_e32 v2, 2, v80
	v_lshl_add_u64 v[80:81], s[30:31], 0, v[2:3]
	global_load_dword v159, v[24:25], off
	global_load_dword v160, v[80:81], off
	v_or_b32_e32 v80, v22, v40
	v_lshl_or_b32 v2, v80, 14, v82
	v_lshl_add_u64 v[24:25], s[6:7], 0, v[2:3]
	v_lshlrev_b32_e32 v2, 2, v80
	v_lshl_add_u64 v[80:81], s[30:31], 0, v[2:3]
	global_load_dword v162, v[24:25], off
	global_load_dword v163, v[80:81], off
	v_or_b32_e32 v80, v22, v41
	v_lshl_or_b32 v2, v80, 14, v82
	v_lshl_add_u64 v[24:25], s[6:7], 0, v[2:3]
	v_lshlrev_b32_e32 v2, 2, v80
	v_lshl_add_u64 v[80:81], s[30:31], 0, v[2:3]
	global_load_dword v165, v[24:25], off
	global_load_dword v166, v[80:81], off
	v_or_b32_e32 v80, v22, v43
	v_lshl_or_b32 v2, v80, 14, v82
	v_lshl_add_u64 v[24:25], s[6:7], 0, v[2:3]
	v_lshlrev_b32_e32 v2, 2, v80
	v_lshl_add_u64 v[80:81], s[30:31], 0, v[2:3]
	global_load_dword v169, v[24:25], off
	global_load_dword v170, v[80:81], off
	v_or_b32_e32 v80, v22, v46
	v_lshl_or_b32 v2, v80, 14, v82
	v_lshl_add_u64 v[24:25], s[6:7], 0, v[2:3]
	v_lshlrev_b32_e32 v2, 2, v80
	v_lshl_add_u64 v[80:81], s[30:31], 0, v[2:3]
	global_load_dword v172, v[24:25], off
	global_load_dword v173, v[80:81], off
	v_or_b32_e32 v80, v22, v48
	v_lshl_or_b32 v2, v80, 14, v82
	v_lshl_add_u64 v[24:25], s[6:7], 0, v[2:3]
	v_lshlrev_b32_e32 v2, 2, v80
	v_lshl_add_u64 v[80:81], s[30:31], 0, v[2:3]
	global_load_dword v175, v[24:25], off
	global_load_dword v176, v[80:81], off
	v_or_b32_e32 v80, v22, v49
	v_lshl_or_b32 v2, v80, 14, v82
	v_lshl_add_u64 v[24:25], s[6:7], 0, v[2:3]
	v_lshlrev_b32_e32 v2, 2, v80
	v_lshl_add_u64 v[80:81], s[30:31], 0, v[2:3]
	global_load_dword v178, v[24:25], off
	global_load_dword v179, v[80:81], off
	v_or_b32_e32 v80, v22, v50
	v_lshl_or_b32 v2, v80, 14, v82
	v_lshl_add_u64 v[24:25], s[6:7], 0, v[2:3]
	v_lshlrev_b32_e32 v2, 2, v80
	v_lshl_add_u64 v[80:81], s[30:31], 0, v[2:3]
	global_load_dword v181, v[24:25], off
	global_load_dword v182, v[80:81], off
	v_or_b32_e32 v80, v22, v52
	v_lshl_or_b32 v2, v80, 14, v82
	v_lshl_add_u64 v[24:25], s[6:7], 0, v[2:3]
	v_lshlrev_b32_e32 v2, 2, v80
	v_lshl_add_u64 v[80:81], s[30:31], 0, v[2:3]
	global_load_dword v184, v[24:25], off
	global_load_dword v185, v[80:81], off
	v_or_b32_e32 v80, v22, v54
	v_lshl_or_b32 v2, v80, 14, v82
	v_lshl_add_u64 v[24:25], s[6:7], 0, v[2:3]
	v_lshlrev_b32_e32 v2, 2, v80
	v_lshl_add_u64 v[80:81], s[30:31], 0, v[2:3]
	global_load_dword v188, v[24:25], off
	global_load_dword v189, v[80:81], off
	v_or_b32_e32 v80, v22, v55
	v_lshl_or_b32 v2, v80, 14, v82
	v_lshl_add_u64 v[24:25], s[6:7], 0, v[2:3]
	v_lshlrev_b32_e32 v2, 2, v80
	v_lshl_add_u64 v[80:81], s[30:31], 0, v[2:3]
	global_load_dword v191, v[24:25], off
	global_load_dword v192, v[80:81], off
	v_or_b32_e32 v80, v22, v56
	v_lshl_or_b32 v2, v80, 14, v82
	v_lshl_add_u64 v[24:25], s[6:7], 0, v[2:3]
	v_lshlrev_b32_e32 v2, 2, v80
	v_lshl_add_u64 v[80:81], s[30:31], 0, v[2:3]
	global_load_dword v194, v[24:25], off
	global_load_dword v195, v[80:81], off
	v_or_b32_e32 v80, v22, v57
	v_lshl_or_b32 v2, v80, 14, v82
	v_lshl_add_u64 v[24:25], s[6:7], 0, v[2:3]
	v_lshlrev_b32_e32 v2, 2, v80
	v_lshl_add_u64 v[80:81], s[30:31], 0, v[2:3]
	global_load_dword v197, v[24:25], off
	global_load_dword v198, v[80:81], off
	v_or_b32_e32 v80, v22, v58
	v_lshl_or_b32 v2, v80, 14, v82
	v_lshl_add_u64 v[24:25], s[6:7], 0, v[2:3]
	v_lshlrev_b32_e32 v2, 2, v80
	v_lshl_add_u64 v[80:81], s[30:31], 0, v[2:3]
	global_load_dword v209, v[24:25], off
	global_load_dword v210, v[80:81], off
	v_or_b32_e32 v80, v22, v59
	v_lshl_or_b32 v2, v80, 14, v82
	v_lshl_add_u64 v[24:25], s[6:7], 0, v[2:3]
	v_lshlrev_b32_e32 v2, 2, v80
	v_lshl_add_u64 v[80:81], s[30:31], 0, v[2:3]
	global_load_dword v212, v[24:25], off
	global_load_dword v213, v[80:81], off
	v_or_b32_e32 v80, v22, v61
	v_lshl_or_b32 v2, v80, 14, v82
	v_lshl_add_u64 v[24:25], s[6:7], 0, v[2:3]
	v_lshlrev_b32_e32 v2, 2, v80
	v_lshl_add_u64 v[80:81], s[30:31], 0, v[2:3]
	v_or_b32_e32 v84, v23, v70
	global_load_dword v216, v[24:25], off
	global_load_dword v217, v[80:81], off
	v_or_b32_e32 v80, v22, v62
	v_lshl_or_b32 v2, v80, 14, v82
	v_lshl_add_u64 v[24:25], s[6:7], 0, v[2:3]
	v_lshlrev_b32_e32 v2, 2, v80
	v_lshl_add_u64 v[80:81], s[30:31], 0, v[2:3]
	global_load_dword v219, v[24:25], off
	global_load_dword v220, v[80:81], off
	v_or_b32_e32 v80, v22, v63
	v_lshl_or_b32 v2, v80, 14, v82
	v_lshl_add_u64 v[24:25], s[6:7], 0, v[2:3]
	v_lshlrev_b32_e32 v2, 2, v80
	v_lshl_add_u64 v[80:81], s[30:31], 0, v[2:3]
	global_load_dword v222, v[24:25], off
	global_load_dword v223, v[80:81], off
	v_or_b32_e32 v80, v22, v64
	v_lshl_or_b32 v2, v80, 14, v82
	v_lshl_add_u64 v[24:25], s[6:7], 0, v[2:3]
	v_lshlrev_b32_e32 v2, 2, v80
	v_lshl_add_u64 v[80:81], s[30:31], 0, v[2:3]
	global_load_dword v225, v[24:25], off
	global_load_dword v226, v[80:81], off
	v_or_b32_e32 v80, v22, v65
	v_lshl_or_b32 v2, v80, 14, v82
	v_lshl_add_u64 v[24:25], s[6:7], 0, v[2:3]
	v_lshlrev_b32_e32 v2, 2, v80
	v_lshl_add_u64 v[80:81], s[30:31], 0, v[2:3]
	global_load_dword v228, v[24:25], off
	global_load_dword v229, v[80:81], off
	v_or_b32_e32 v80, v22, v66
	v_lshl_or_b32 v2, v80, 14, v82
	v_lshl_add_u64 v[24:25], s[6:7], 0, v[2:3]
	v_lshlrev_b32_e32 v2, 2, v80
	v_lshl_add_u64 v[80:81], s[30:31], 0, v[2:3]
	global_load_dword v231, v[24:25], off
	global_load_dword v232, v[80:81], off
	v_or_b32_e32 v80, v22, v67
	v_lshl_or_b32 v2, v80, 14, v82
	v_lshl_add_u64 v[24:25], s[6:7], 0, v[2:3]
	v_lshlrev_b32_e32 v2, 2, v80
	v_lshl_add_u64 v[80:81], s[30:31], 0, v[2:3]
	global_load_dword v234, v[24:25], off
	s_nop 0
	global_load_dword v235, v[80:81], off
	s_waitcnt vmcnt(0) lgkmcnt(0)
	v_add_u32_e32 v129, v27, v28
	v_add_u32_e32 v214, v27, v60
	v_mul_f32_e32 v126, v127, v128
	ds_write_b32 v129, v126
	v_mul_f32_e32 v130, v131, v132
	ds_write_b32 v129, v130 offset:264
	v_mul_f32_e32 v133, v134, v135
	ds_write_b32 v129, v133 offset:528
	v_mul_f32_e32 v136, v137, v138
	ds_write_b32 v129, v136 offset:792
	v_mul_f32_e32 v139, v140, v141
	ds_write_b32 v129, v139 offset:1056
	v_mul_f32_e32 v142, v143, v144
	ds_write_b32 v129, v142 offset:1320
	v_add_u32_e32 v148, v27, v35
	v_mul_f32_e32 v145, v146, v147
	ds_write_b32 v148, v145
	v_mul_f32_e32 v149, v150, v151
	ds_write_b32 v148, v149 offset:264
	v_mul_f32_e32 v152, v153, v154
	ds_write_b32 v148, v152 offset:528
	v_mul_f32_e32 v155, v156, v157
	ds_write_b32 v148, v155 offset:792
	v_mul_f32_e32 v158, v159, v160
	ds_write_b32 v148, v158 offset:1056
	v_mul_f32_e32 v161, v162, v163
	ds_write_b32 v148, v161 offset:1320
	v_add_u32_e32 v167, v27, v42
	v_mul_f32_e32 v164, v165, v166
	ds_write_b32 v167, v164
	v_mul_f32_e32 v168, v169, v170
	ds_write_b32 v167, v168 offset:264
	v_mul_f32_e32 v171, v172, v173
	ds_write_b32 v167, v171 offset:528
	v_mul_f32_e32 v174, v175, v176
	ds_write_b32 v167, v174 offset:792
	v_mul_f32_e32 v177, v178, v179
	ds_write_b32 v167, v177 offset:1056
	v_mul_f32_e32 v180, v181, v182
	ds_write_b32 v167, v180 offset:1320
	v_add_u32_e32 v186, v27, v53
	v_mul_f32_e32 v183, v184, v185
	ds_write_b32 v186, v183
	v_mul_f32_e32 v187, v188, v189
	ds_write_b32 v186, v187 offset:264
	v_mul_f32_e32 v190, v191, v192
	ds_write_b32 v186, v190 offset:528
	v_mul_f32_e32 v193, v194, v195
	ds_write_b32 v186, v193 offset:792
	v_mul_f32_e32 v196, v197, v198
	ds_write_b32 v186, v196 offset:1056
	v_mul_f32_e32 v199, v209, v210
	ds_write_b32 v186, v199 offset:1320
	v_mul_f32_e32 v211, v212, v213
	ds_write_b32 v214, v211
	v_mul_f32_e32 v215, v216, v217
	ds_write_b32 v214, v215 offset:264
	v_mul_f32_e32 v218, v219, v220
	ds_write_b32 v214, v218 offset:528
	v_mul_f32_e32 v221, v222, v223
	ds_write_b32 v214, v221 offset:792
	v_mul_f32_e32 v224, v225, v226
	ds_write_b32 v214, v224 offset:1056
	v_mul_f32_e32 v227, v228, v229
	ds_write_b32 v214, v227 offset:1320
	v_mul_f32_e32 v230, v231, v232
	ds_write_b32 v214, v230 offset:1584
	v_mul_f32_e32 v233, v234, v235
	ds_write_b32 v214, v233 offset:1848
	v_or_b32_e32 v79, v23, v68
	v_lshlrev_b32_e32 v2, 1, v22
	v_lshl_add_u64 v[80:81], v[16:17], 0, v[2:3]
	v_lshlrev_b32_e32 v2, 11, v79
	v_lshl_add_u64 v[82:83], v[80:81], 0, v[2:3]
	v_lshlrev_b32_e32 v2, 11, v84
	v_or_b32_e32 v23, v23, v72
	v_lshl_add_u64 v[84:85], v[80:81], 0, v[2:3]
	v_lshlrev_b32_e32 v2, 11, v86
	v_lshl_add_u64 v[86:87], v[80:81], 0, v[2:3]
	v_lshlrev_b32_e32 v2, 11, v23
	v_lshl_add_u64 v[80:81], v[80:81], 0, v[2:3]
	s_waitcnt lgkmcnt(0)
	ds_read_b32 v22, v69
	ds_read_b32 v23, v69 offset:132
	ds_read_b32 v24, v69 offset:264
	ds_read_b32 v25, v69 offset:396
	ds_read_b32 v79, v69 offset:528
	ds_read_b32 v88, v69 offset:660
	ds_read_b32 v89, v69 offset:792
	ds_read_b32 v90, v69 offset:924
	s_waitcnt lgkmcnt(7)
	v_bfe_u32 v91, v22, 16, 1
	s_waitcnt lgkmcnt(5)
	v_bfe_u32 v93, v24, 16, 1
	s_waitcnt lgkmcnt(3)
	v_bfe_u32 v95, v79, 16, 1
	s_waitcnt lgkmcnt(1)
	v_bfe_u32 v97, v89, 16, 1
	v_bfe_u32 v92, v23, 16, 1
	v_bfe_u32 v94, v25, 16, 1
	v_bfe_u32 v96, v88, 16, 1
	s_waitcnt lgkmcnt(0)
	v_bfe_u32 v98, v90, 16, 1
	v_add3_u32 v22, v22, v91, s56
	v_add3_u32 v24, v24, v93, s56
	v_add3_u32 v79, v79, v95, s56
	v_add3_u32 v89, v89, v97, s56
	v_add3_u32 v23, v23, v92, s56
	v_add3_u32 v25, v25, v94, s56
	v_add3_u32 v88, v88, v96, s56
	v_add3_u32 v90, v90, v98, s56
	v_lshrrev_b32_e32 v22, 16, v22
	v_lshrrev_b32_e32 v24, 16, v24
	v_lshrrev_b32_e32 v79, 16, v79
	v_lshrrev_b32_e32 v89, 16, v89
	v_and_or_b32 v22, v23, s57, v22
	v_and_or_b32 v23, v25, s57, v24
	v_and_or_b32 v24, v88, s57, v79
	v_and_or_b32 v25, v90, s57, v89
	flat_store_dwordx4 v[82:83], v[22:25]
	ds_read_b32 v22, v69 offset:32
	ds_read_b32 v23, v69 offset:164
	ds_read_b32 v24, v69 offset:296
	ds_read_b32 v25, v69 offset:428
	ds_read_b32 v79, v69 offset:560
	ds_read_b32 v82, v69 offset:692
	ds_read_b32 v83, v69 offset:824
	ds_read_b32 v88, v69 offset:956
	s_waitcnt lgkmcnt(0)
	v_bfe_u32 v89, v22, 16, 1
	v_bfe_u32 v91, v24, 16, 1
	v_bfe_u32 v93, v79, 16, 1
	v_bfe_u32 v95, v83, 16, 1
	v_bfe_u32 v90, v23, 16, 1
	v_bfe_u32 v92, v25, 16, 1
	v_bfe_u32 v94, v82, 16, 1
	v_bfe_u32 v96, v88, 16, 1
	v_add3_u32 v22, v22, v89, s56
	v_add3_u32 v24, v24, v91, s56
	v_add3_u32 v79, v79, v93, s56
	v_add3_u32 v83, v83, v95, s56
	v_add3_u32 v23, v23, v90, s56
	v_add3_u32 v25, v25, v92, s56
	v_add3_u32 v82, v82, v94, s56
	v_add3_u32 v88, v88, v96, s56
	v_lshrrev_b32_e32 v22, 16, v22
	v_lshrrev_b32_e32 v24, 16, v24
	v_lshrrev_b32_e32 v79, 16, v79
	v_lshrrev_b32_e32 v83, 16, v83
	v_and_or_b32 v22, v23, s57, v22
	v_and_or_b32 v23, v25, s57, v24
	v_and_or_b32 v24, v82, s57, v79
	v_and_or_b32 v25, v88, s57, v83
	flat_store_dwordx4 v[84:85], v[22:25]
	ds_read_b32 v22, v69 offset:64
	ds_read_b32 v23, v69 offset:196
	ds_read_b32 v24, v69 offset:328
	ds_read_b32 v25, v69 offset:460
	ds_read_b32 v79, v69 offset:592
	ds_read_b32 v82, v69 offset:724
	ds_read_b32 v83, v69 offset:856
	ds_read_b32 v84, v69 offset:988
	s_waitcnt lgkmcnt(0)
	v_bfe_u32 v85, v22, 16, 1
	v_bfe_u32 v89, v24, 16, 1
	v_bfe_u32 v91, v79, 16, 1
	v_bfe_u32 v93, v83, 16, 1
	v_bfe_u32 v88, v23, 16, 1
	v_bfe_u32 v90, v25, 16, 1
	v_bfe_u32 v92, v82, 16, 1
	v_bfe_u32 v94, v84, 16, 1
	v_add3_u32 v22, v22, v85, s56
	v_add3_u32 v24, v24, v89, s56
	v_add3_u32 v79, v79, v91, s56
	v_add3_u32 v83, v83, v93, s56
	v_add3_u32 v23, v23, v88, s56
	v_add3_u32 v25, v25, v90, s56
	v_add3_u32 v82, v82, v92, s56
	v_add3_u32 v84, v84, v94, s56
	v_lshrrev_b32_e32 v22, 16, v22
	v_lshrrev_b32_e32 v24, 16, v24
	v_lshrrev_b32_e32 v79, 16, v79
	v_lshrrev_b32_e32 v83, 16, v83
	v_and_or_b32 v22, v23, s57, v22
	v_and_or_b32 v23, v25, s57, v24
	v_and_or_b32 v24, v82, s57, v79
	v_and_or_b32 v25, v84, s57, v83
	flat_store_dwordx4 v[86:87], v[22:25]
	ds_read_b32 v22, v69 offset:96
	ds_read_b32 v23, v69 offset:228
	ds_read_b32 v24, v69 offset:360
	ds_read_b32 v25, v69 offset:492
	ds_read_b32 v79, v69 offset:624
	ds_read_b32 v82, v69 offset:756
	ds_read_b32 v83, v69 offset:888
	ds_read_b32 v84, v69 offset:1020
	s_waitcnt lgkmcnt(0)
	v_bfe_u32 v85, v22, 16, 1
	v_bfe_u32 v87, v24, 16, 1
	v_bfe_u32 v89, v79, 16, 1
	v_bfe_u32 v91, v83, 16, 1
	v_bfe_u32 v86, v23, 16, 1
	v_bfe_u32 v88, v25, 16, 1
	v_bfe_u32 v90, v82, 16, 1
	v_bfe_u32 v92, v84, 16, 1
	v_add3_u32 v22, v22, v85, s56
	v_add3_u32 v24, v24, v87, s56
	v_add3_u32 v79, v79, v89, s56
	v_add3_u32 v83, v83, v91, s56
	v_add3_u32 v23, v23, v86, s56
	v_add3_u32 v25, v25, v88, s56
	v_add3_u32 v82, v82, v90, s56
	v_add3_u32 v84, v84, v92, s56
	v_lshrrev_b32_e32 v22, 16, v22
	v_lshrrev_b32_e32 v24, 16, v24
	v_lshrrev_b32_e32 v79, 16, v79
	v_lshrrev_b32_e32 v83, 16, v83
	v_and_or_b32 v22, v23, s57, v22
	v_and_or_b32 v23, v25, s57, v24
	v_and_or_b32 v24, v82, s57, v79
	v_and_or_b32 v25, v84, s57, v83
	flat_store_dwordx4 v[80:81], v[22:25]
	s_waitcnt lgkmcnt(0)

.LBB0_29:
	s_andn2_saveexec_b64 s[38:39], s[38:39]
	s_cbranch_execz .LBB0_31
	v_add_u32_e32 v2, 0x4800, v77
	v_and_b32_e32 v25, 0x3e0, v74
	v_and_b32_e32 v24, 0x1ffc0, v2
	v_or_b32_e32 v2, v25, v26
	v_or_b32_e32 v22, v24, v19
	v_lshlrev_b32_e32 v79, 2, v2
	v_lshl_or_b32 v2, v22, 12, v79
	v_lshl_add_u64 v[22:23], s[4:5], 0, v[2:3]
	global_load_dword v126, v[22:23], off
	v_or_b32_e32 v2, v24, v29
	v_lshl_or_b32 v2, v2, 12, v79
	v_lshl_add_u64 v[22:23], s[4:5], 0, v[2:3]
	v_or_b32_e32 v2, v24, v30
	v_lshl_or_b32 v2, v2, 12, v79
	v_or_b32_e32 v86, v25, v71
	global_load_dword v128, v[22:23], off
	v_lshl_add_u64 v[22:23], s[4:5], 0, v[2:3]
	v_or_b32_e32 v2, v24, v31
	v_lshl_or_b32 v2, v2, 12, v79
	global_load_dword v129, v[22:23], off
	v_lshl_add_u64 v[22:23], s[4:5], 0, v[2:3]
	v_or_b32_e32 v2, v24, v32
	v_lshl_or_b32 v2, v2, 12, v79
	global_load_dword v130, v[22:23], off
	v_lshl_add_u64 v[22:23], s[4:5], 0, v[2:3]
	v_or_b32_e32 v2, v24, v33
	v_lshl_or_b32 v2, v2, 12, v79
	global_load_dword v131, v[22:23], off
	v_lshl_add_u64 v[22:23], s[4:5], 0, v[2:3]
	v_or_b32_e32 v2, v24, v34
	v_lshl_or_b32 v2, v2, 12, v79
	global_load_dword v132, v[22:23], off
	v_lshl_add_u64 v[22:23], s[4:5], 0, v[2:3]
	v_or_b32_e32 v2, v24, v36
	v_lshl_or_b32 v2, v2, 12, v79
	global_load_dword v133, v[22:23], off
	v_lshl_add_u64 v[22:23], s[4:5], 0, v[2:3]
	v_or_b32_e32 v2, v24, v37
	v_lshl_or_b32 v2, v2, 12, v79
	global_load_dword v135, v[22:23], off
	v_lshl_add_u64 v[22:23], s[4:5], 0, v[2:3]
	v_or_b32_e32 v2, v24, v38
	v_lshl_or_b32 v2, v2, 12, v79
	global_load_dword v136, v[22:23], off
	v_lshl_add_u64 v[22:23], s[4:5], 0, v[2:3]
	v_or_b32_e32 v2, v24, v39
	v_lshl_or_b32 v2, v2, 12, v79
	global_load_dword v137, v[22:23], off
	v_lshl_add_u64 v[22:23], s[4:5], 0, v[2:3]
	v_or_b32_e32 v2, v24, v40
	v_lshl_or_b32 v2, v2, 12, v79
	global_load_dword v138, v[22:23], off
	v_lshl_add_u64 v[22:23], s[4:5], 0, v[2:3]
	v_or_b32_e32 v2, v24, v41
	v_lshl_or_b32 v2, v2, 12, v79
	global_load_dword v139, v[22:23], off
	v_lshl_add_u64 v[22:23], s[4:5], 0, v[2:3]
	v_or_b32_e32 v2, v24, v43
	v_lshl_or_b32 v2, v2, 12, v79
	global_load_dword v140, v[22:23], off
	v_lshl_add_u64 v[22:23], s[4:5], 0, v[2:3]
	v_or_b32_e32 v2, v24, v46
	v_lshl_or_b32 v2, v2, 12, v79
	global_load_dword v142, v[22:23], off
	v_lshl_add_u64 v[22:23], s[4:5], 0, v[2:3]
	v_or_b32_e32 v2, v24, v48
	v_lshl_or_b32 v2, v2, 12, v79
	global_load_dword v143, v[22:23], off
	v_lshl_add_u64 v[22:23], s[4:5], 0, v[2:3]
	v_or_b32_e32 v2, v24, v49
	v_lshl_or_b32 v2, v2, 12, v79
	global_load_dword v144, v[22:23], off
	v_lshl_add_u64 v[22:23], s[4:5], 0, v[2:3]
	v_or_b32_e32 v2, v24, v50
	v_lshl_or_b32 v2, v2, 12, v79
	global_load_dword v145, v[22:23], off
	v_lshl_add_u64 v[22:23], s[4:5], 0, v[2:3]
	v_or_b32_e32 v2, v24, v52
	v_lshl_or_b32 v2, v2, 12, v79
	global_load_dword v146, v[22:23], off
	v_lshl_add_u64 v[22:23], s[4:5], 0, v[2:3]
	v_or_b32_e32 v2, v24, v54
	v_lshl_or_b32 v2, v2, 12, v79
	global_load_dword v147, v[22:23], off
	v_lshl_add_u64 v[22:23], s[4:5], 0, v[2:3]
	v_or_b32_e32 v2, v24, v55
	v_lshl_or_b32 v2, v2, 12, v79
	global_load_dword v149, v[22:23], off
	v_lshl_add_u64 v[22:23], s[4:5], 0, v[2:3]
	v_or_b32_e32 v2, v24, v56
	v_lshl_or_b32 v2, v2, 12, v79
	global_load_dword v150, v[22:23], off
	v_lshl_add_u64 v[22:23], s[4:5], 0, v[2:3]
	v_or_b32_e32 v2, v24, v57
	v_lshl_or_b32 v2, v2, 12, v79
	global_load_dword v151, v[22:23], off
	v_lshl_add_u64 v[22:23], s[4:5], 0, v[2:3]
	v_or_b32_e32 v2, v24, v58
	v_lshl_or_b32 v2, v2, 12, v79
	global_load_dword v152, v[22:23], off
	v_lshl_add_u64 v[22:23], s[4:5], 0, v[2:3]
	v_or_b32_e32 v2, v24, v59
	v_lshl_or_b32 v2, v2, 12, v79
	global_load_dword v153, v[22:23], off
	v_lshl_add_u64 v[22:23], s[4:5], 0, v[2:3]
	v_or_b32_e32 v2, v24, v61
	v_lshl_or_b32 v2, v2, 12, v79
	global_load_dword v154, v[22:23], off
	v_lshl_add_u64 v[22:23], s[4:5], 0, v[2:3]
	v_or_b32_e32 v2, v24, v62
	v_lshl_or_b32 v2, v2, 12, v79
	global_load_dword v156, v[22:23], off
	v_lshl_add_u64 v[22:23], s[4:5], 0, v[2:3]
	v_or_b32_e32 v2, v24, v63
	v_lshl_or_b32 v2, v2, 12, v79
	global_load_dword v157, v[22:23], off
	v_lshl_add_u64 v[22:23], s[4:5], 0, v[2:3]
	v_or_b32_e32 v2, v24, v64
	v_lshl_or_b32 v2, v2, 12, v79
	global_load_dword v158, v[22:23], off
	v_lshl_add_u64 v[22:23], s[4:5], 0, v[2:3]
	v_or_b32_e32 v2, v24, v65
	v_lshl_or_b32 v2, v2, 12, v79
	global_load_dword v159, v[22:23], off
	v_lshl_add_u64 v[22:23], s[4:5], 0, v[2:3]
	v_or_b32_e32 v2, v24, v66
	v_lshl_or_b32 v2, v2, 12, v79
	global_load_dword v160, v[22:23], off
	v_lshl_add_u64 v[22:23], s[4:5], 0, v[2:3]
	v_or_b32_e32 v2, v24, v67
	v_lshl_or_b32 v2, v2, 12, v79
	v_or_b32_e32 v79, v25, v70
	global_load_dword v161, v[22:23], off
	v_lshl_add_u64 v[22:23], s[4:5], 0, v[2:3]
	v_lshlrev_b32_e32 v2, 1, v24
	global_load_dword v162, v[22:23], off
	s_waitcnt vmcnt(0) lgkmcnt(0)
	v_add_u32_e32 v127, v27, v28
	v_add_u32_e32 v155, v27, v60
	ds_write_b32 v127, v126
	ds_write_b32 v127, v128 offset:264
	ds_write_b32 v127, v129 offset:528
	ds_write_b32 v127, v130 offset:792
	ds_write_b32 v127, v131 offset:1056
	ds_write_b32 v127, v132 offset:1320
	v_add_u32_e32 v134, v27, v35
	ds_write_b32 v134, v133
	ds_write_b32 v134, v135 offset:264
	ds_write_b32 v134, v136 offset:528
	ds_write_b32 v134, v137 offset:792
	ds_write_b32 v134, v138 offset:1056
	ds_write_b32 v134, v139 offset:1320
	v_add_u32_e32 v141, v27, v42
	ds_write_b32 v141, v140
	ds_write_b32 v141, v142 offset:264
	ds_write_b32 v141, v143 offset:528
	ds_write_b32 v141, v144 offset:792
	ds_write_b32 v141, v145 offset:1056
	ds_write_b32 v141, v146 offset:1320
	v_add_u32_e32 v148, v27, v53
	ds_write_b32 v148, v147
	ds_write_b32 v148, v149 offset:264
	ds_write_b32 v148, v150 offset:528
	ds_write_b32 v148, v151 offset:792
	ds_write_b32 v148, v152 offset:1056
	ds_write_b32 v148, v153 offset:1320
	ds_write_b32 v155, v154
	ds_write_b32 v155, v156 offset:264
	ds_write_b32 v155, v157 offset:528
	ds_write_b32 v155, v158 offset:792
	ds_write_b32 v155, v159 offset:1056
	ds_write_b32 v155, v160 offset:1320
	ds_write_b32 v155, v161 offset:1584
	ds_write_b32 v155, v162 offset:1848
	v_or_b32_e32 v23, v25, v68
	v_lshl_add_u64 v[80:81], v[20:21], 0, v[2:3]
	v_lshlrev_b32_e32 v2, 12, v23
	v_lshl_add_u64 v[82:83], v[80:81], 0, v[2:3]
	v_lshlrev_b32_e32 v2, 12, v79
	v_or_b32_e32 v25, v25, v72
	v_lshl_add_u64 v[84:85], v[80:81], 0, v[2:3]
	v_lshlrev_b32_e32 v2, 12, v86
	v_lshl_add_u64 v[86:87], v[80:81], 0, v[2:3]
	v_lshlrev_b32_e32 v2, 12, v25
	v_lshl_add_u64 v[80:81], v[80:81], 0, v[2:3]
	s_waitcnt lgkmcnt(0)
	ds_read_b32 v22, v69
	ds_read_b32 v23, v69 offset:132
	ds_read_b32 v24, v69 offset:264
	ds_read_b32 v25, v69 offset:396
	ds_read_b32 v79, v69 offset:528
	ds_read_b32 v88, v69 offset:660
	ds_read_b32 v89, v69 offset:792
	ds_read_b32 v90, v69 offset:924
	s_waitcnt lgkmcnt(7)
	v_bfe_u32 v91, v22, 16, 1
	s_waitcnt lgkmcnt(5)
	v_bfe_u32 v93, v24, 16, 1
	s_waitcnt lgkmcnt(3)
	v_bfe_u32 v95, v79, 16, 1
	s_waitcnt lgkmcnt(1)
	v_bfe_u32 v97, v89, 16, 1
	v_bfe_u32 v92, v23, 16, 1
	v_bfe_u32 v94, v25, 16, 1
	v_bfe_u32 v96, v88, 16, 1
	s_waitcnt lgkmcnt(0)
	v_bfe_u32 v98, v90, 16, 1
	v_add3_u32 v22, v22, v91, s56
	v_add3_u32 v24, v24, v93, s56
	v_add3_u32 v79, v79, v95, s56
	v_add3_u32 v89, v89, v97, s56
	v_add3_u32 v23, v23, v92, s56
	v_add3_u32 v25, v25, v94, s56
	v_add3_u32 v88, v88, v96, s56
	v_add3_u32 v90, v90, v98, s56
	v_lshrrev_b32_e32 v22, 16, v22
	v_lshrrev_b32_e32 v24, 16, v24
	v_lshrrev_b32_e32 v79, 16, v79
	v_lshrrev_b32_e32 v89, 16, v89
	v_and_or_b32 v22, v23, s57, v22
	v_and_or_b32 v23, v25, s57, v24
	v_and_or_b32 v24, v88, s57, v79
	v_and_or_b32 v25, v90, s57, v89
	flat_store_dwordx4 v[82:83], v[22:25]
	ds_read_b32 v22, v69 offset:32
	ds_read_b32 v23, v69 offset:164
	ds_read_b32 v24, v69 offset:296
	ds_read_b32 v25, v69 offset:428
	ds_read_b32 v79, v69 offset:560
	ds_read_b32 v82, v69 offset:692
	ds_read_b32 v83, v69 offset:824
	ds_read_b32 v88, v69 offset:956
	s_waitcnt lgkmcnt(0)
	v_bfe_u32 v89, v22, 16, 1
	v_bfe_u32 v91, v24, 16, 1
	v_bfe_u32 v93, v79, 16, 1
	v_bfe_u32 v95, v83, 16, 1
	v_bfe_u32 v90, v23, 16, 1
	v_bfe_u32 v92, v25, 16, 1
	v_bfe_u32 v94, v82, 16, 1
	v_bfe_u32 v96, v88, 16, 1
	v_add3_u32 v22, v22, v89, s56
	v_add3_u32 v24, v24, v91, s56
	v_add3_u32 v79, v79, v93, s56
	v_add3_u32 v83, v83, v95, s56
	v_add3_u32 v23, v23, v90, s56
	v_add3_u32 v25, v25, v92, s56
	v_add3_u32 v82, v82, v94, s56
	v_add3_u32 v88, v88, v96, s56
	v_lshrrev_b32_e32 v22, 16, v22
	v_lshrrev_b32_e32 v24, 16, v24
	v_lshrrev_b32_e32 v79, 16, v79
	v_lshrrev_b32_e32 v83, 16, v83
	v_and_or_b32 v22, v23, s57, v22
	v_and_or_b32 v23, v25, s57, v24
	v_and_or_b32 v24, v82, s57, v79
	v_and_or_b32 v25, v88, s57, v83
	flat_store_dwordx4 v[84:85], v[22:25]
	ds_read_b32 v22, v69 offset:64
	ds_read_b32 v23, v69 offset:196
	ds_read_b32 v24, v69 offset:328
	ds_read_b32 v25, v69 offset:460
	ds_read_b32 v79, v69 offset:592
	ds_read_b32 v82, v69 offset:724
	ds_read_b32 v83, v69 offset:856
	ds_read_b32 v84, v69 offset:988
	s_waitcnt lgkmcnt(0)
	v_bfe_u32 v85, v22, 16, 1
	v_bfe_u32 v89, v24, 16, 1
	v_bfe_u32 v91, v79, 16, 1
	v_bfe_u32 v93, v83, 16, 1
	v_bfe_u32 v88, v23, 16, 1
	v_bfe_u32 v90, v25, 16, 1
	v_bfe_u32 v92, v82, 16, 1
	v_bfe_u32 v94, v84, 16, 1
	v_add3_u32 v22, v22, v85, s56
	v_add3_u32 v24, v24, v89, s56
	v_add3_u32 v79, v79, v91, s56
	v_add3_u32 v83, v83, v93, s56
	v_add3_u32 v23, v23, v88, s56
	v_add3_u32 v25, v25, v90, s56
	v_add3_u32 v82, v82, v92, s56
	v_add3_u32 v84, v84, v94, s56
	v_lshrrev_b32_e32 v22, 16, v22
	v_lshrrev_b32_e32 v24, 16, v24
	v_lshrrev_b32_e32 v79, 16, v79
	v_lshrrev_b32_e32 v83, 16, v83
	v_and_or_b32 v22, v23, s57, v22
	v_and_or_b32 v23, v25, s57, v24
	v_and_or_b32 v24, v82, s57, v79
	v_and_or_b32 v25, v84, s57, v83
	flat_store_dwordx4 v[86:87], v[22:25]
	ds_read_b32 v22, v69 offset:96
	ds_read_b32 v23, v69 offset:228
	ds_read_b32 v24, v69 offset:360
	ds_read_b32 v25, v69 offset:492
	ds_read_b32 v79, v69 offset:624
	ds_read_b32 v82, v69 offset:756
	ds_read_b32 v83, v69 offset:888
	ds_read_b32 v84, v69 offset:1020
	s_waitcnt lgkmcnt(0)
	v_bfe_u32 v85, v22, 16, 1
	v_bfe_u32 v87, v24, 16, 1
	v_bfe_u32 v89, v79, 16, 1
	v_bfe_u32 v91, v83, 16, 1
	v_bfe_u32 v86, v23, 16, 1
	v_bfe_u32 v88, v25, 16, 1
	v_bfe_u32 v90, v82, 16, 1
	v_bfe_u32 v92, v84, 16, 1
	v_add3_u32 v22, v22, v85, s56
	v_add3_u32 v24, v24, v87, s56
	v_add3_u32 v79, v79, v89, s56
	v_add3_u32 v83, v83, v91, s56
	v_add3_u32 v23, v23, v86, s56
	v_add3_u32 v25, v25, v88, s56
	v_add3_u32 v82, v82, v90, s56
	v_add3_u32 v84, v84, v92, s56
	v_lshrrev_b32_e32 v22, 16, v22
	v_lshrrev_b32_e32 v24, 16, v24
	v_lshrrev_b32_e32 v79, 16, v79
	v_lshrrev_b32_e32 v83, 16, v83
	v_and_or_b32 v22, v23, s57, v22
	v_and_or_b32 v23, v25, s57, v24
	v_and_or_b32 v24, v82, s57, v79
	v_and_or_b32 v25, v84, s57, v83
	flat_store_dwordx4 v[80:81], v[22:25]
	s_waitcnt lgkmcnt(0)

.LBB0_32:
	s_andn2_saveexec_b64 s[36:37], s[36:37]
	s_cbranch_execz .LBB0_9
	v_ashrrev_i32_e32 v2, 31, v78
	v_add_u32_sdwa v2, v78, v2 dst_sel:DWORD dst_unused:UNUSED_PAD src0_sel:DWORD src1_sel:BYTE_3
	v_ashrrev_i32_e32 v2, 8, v2
	v_mul_i32_i24_e32 v23, 0x100, v2
	v_lshlrev_b32_e32 v22, 6, v2
	v_lshlrev_b32_e32 v2, 5, v23
	v_sub_u32_e32 v24, v74, v2
	v_or_b32_e32 v80, v22, v19
	v_ashrrev_i32_e32 v25, 31, v24
	v_ashrrev_i32_e32 v81, 31, v80
	v_lshl_add_u64 v[24:25], v[24:25], 2, v[6:7]
	v_lshlrev_b64 v[80:81], 15, v[80:81]
	v_lshl_add_u64 v[80:81], v[24:25], 0, v[80:81]
	global_load_dword v126, v[80:81], off
	v_or_b32_e32 v80, v22, v29
	v_ashrrev_i32_e32 v81, 31, v80
	v_lshlrev_b64 v[80:81], 15, v[80:81]
	v_lshl_add_u64 v[80:81], v[24:25], 0, v[80:81]
	global_load_dword v128, v[80:81], off
	v_or_b32_e32 v80, v22, v30
	v_ashrrev_i32_e32 v81, 31, v80
	v_lshlrev_b64 v[80:81], 15, v[80:81]
	v_lshl_add_u64 v[80:81], v[24:25], 0, v[80:81]
	global_load_dword v129, v[80:81], off
	v_or_b32_e32 v80, v22, v31
	v_ashrrev_i32_e32 v81, 31, v80
	v_lshlrev_b64 v[80:81], 15, v[80:81]
	v_lshl_add_u64 v[80:81], v[24:25], 0, v[80:81]
	global_load_dword v130, v[80:81], off
	v_or_b32_e32 v80, v22, v32
	v_ashrrev_i32_e32 v81, 31, v80
	v_lshlrev_b64 v[80:81], 15, v[80:81]
	v_lshl_add_u64 v[80:81], v[24:25], 0, v[80:81]
	global_load_dword v131, v[80:81], off
	v_or_b32_e32 v80, v22, v33
	v_ashrrev_i32_e32 v81, 31, v80
	v_lshlrev_b64 v[80:81], 15, v[80:81]
	v_lshl_add_u64 v[80:81], v[24:25], 0, v[80:81]
	global_load_dword v132, v[80:81], off
	v_or_b32_e32 v80, v22, v34
	v_ashrrev_i32_e32 v81, 31, v80
	v_lshlrev_b64 v[80:81], 15, v[80:81]
	v_lshl_add_u64 v[80:81], v[24:25], 0, v[80:81]
	global_load_dword v133, v[80:81], off
	v_or_b32_e32 v80, v22, v36
	v_ashrrev_i32_e32 v81, 31, v80
	v_lshlrev_b64 v[80:81], 15, v[80:81]
	v_lshl_add_u64 v[80:81], v[24:25], 0, v[80:81]
	global_load_dword v135, v[80:81], off
	v_or_b32_e32 v80, v22, v37
	v_ashrrev_i32_e32 v81, 31, v80
	v_lshlrev_b64 v[80:81], 15, v[80:81]
	v_lshl_add_u64 v[80:81], v[24:25], 0, v[80:81]
	global_load_dword v136, v[80:81], off
	v_or_b32_e32 v80, v22, v38
	v_ashrrev_i32_e32 v81, 31, v80
	v_lshlrev_b64 v[80:81], 15, v[80:81]
	v_lshl_add_u64 v[80:81], v[24:25], 0, v[80:81]
	global_load_dword v137, v[80:81], off
	v_or_b32_e32 v80, v22, v39
	v_ashrrev_i32_e32 v81, 31, v80
	v_lshlrev_b64 v[80:81], 15, v[80:81]
	v_lshl_add_u64 v[80:81], v[24:25], 0, v[80:81]
	global_load_dword v138, v[80:81], off
	v_or_b32_e32 v80, v22, v40
	v_ashrrev_i32_e32 v81, 31, v80
	v_lshlrev_b64 v[80:81], 15, v[80:81]
	v_lshl_add_u64 v[80:81], v[24:25], 0, v[80:81]
	global_load_dword v139, v[80:81], off
	v_or_b32_e32 v80, v22, v41
	v_ashrrev_i32_e32 v81, 31, v80
	v_lshlrev_b64 v[80:81], 15, v[80:81]
	v_lshl_add_u64 v[80:81], v[24:25], 0, v[80:81]
	global_load_dword v140, v[80:81], off
	v_or_b32_e32 v80, v22, v43
	v_ashrrev_i32_e32 v81, 31, v80
	v_lshlrev_b64 v[80:81], 15, v[80:81]
	v_lshl_add_u64 v[80:81], v[24:25], 0, v[80:81]
	global_load_dword v142, v[80:81], off
	v_or_b32_e32 v80, v22, v46
	v_ashrrev_i32_e32 v81, 31, v80
	v_lshlrev_b64 v[80:81], 15, v[80:81]
	v_lshl_add_u64 v[80:81], v[24:25], 0, v[80:81]
	global_load_dword v143, v[80:81], off
	v_or_b32_e32 v80, v22, v48
	v_ashrrev_i32_e32 v81, 31, v80
	v_lshlrev_b64 v[80:81], 15, v[80:81]
	v_lshl_add_u64 v[80:81], v[24:25], 0, v[80:81]
	global_load_dword v144, v[80:81], off
	v_or_b32_e32 v80, v22, v49
	v_ashrrev_i32_e32 v81, 31, v80
	v_lshlrev_b64 v[80:81], 15, v[80:81]
	v_lshl_add_u64 v[80:81], v[24:25], 0, v[80:81]
	global_load_dword v145, v[80:81], off
	v_or_b32_e32 v80, v22, v50
	v_ashrrev_i32_e32 v81, 31, v80
	v_lshlrev_b64 v[80:81], 15, v[80:81]
	v_lshl_add_u64 v[80:81], v[24:25], 0, v[80:81]
	global_load_dword v146, v[80:81], off
	v_or_b32_e32 v80, v22, v52
	v_ashrrev_i32_e32 v81, 31, v80
	v_lshlrev_b64 v[80:81], 15, v[80:81]
	v_lshl_add_u64 v[80:81], v[24:25], 0, v[80:81]
	global_load_dword v147, v[80:81], off
	v_or_b32_e32 v80, v22, v54
	v_ashrrev_i32_e32 v81, 31, v80
	v_lshlrev_b64 v[80:81], 15, v[80:81]
	v_lshl_add_u64 v[80:81], v[24:25], 0, v[80:81]
	global_load_dword v149, v[80:81], off
	v_or_b32_e32 v80, v22, v55
	v_ashrrev_i32_e32 v81, 31, v80
	v_lshlrev_b64 v[80:81], 15, v[80:81]
	v_lshl_add_u64 v[80:81], v[24:25], 0, v[80:81]
	global_load_dword v150, v[80:81], off
	v_or_b32_e32 v80, v22, v56
	v_ashrrev_i32_e32 v81, 31, v80
	v_lshlrev_b64 v[80:81], 15, v[80:81]
	v_lshl_add_u64 v[80:81], v[24:25], 0, v[80:81]
	global_load_dword v151, v[80:81], off
	v_or_b32_e32 v80, v22, v57
	v_ashrrev_i32_e32 v81, 31, v80
	v_lshlrev_b64 v[80:81], 15, v[80:81]
	v_lshl_add_u64 v[80:81], v[24:25], 0, v[80:81]
	global_load_dword v152, v[80:81], off
	v_or_b32_e32 v80, v22, v58
	v_ashrrev_i32_e32 v81, 31, v80
	v_lshlrev_b64 v[80:81], 15, v[80:81]
	v_lshl_add_u64 v[80:81], v[24:25], 0, v[80:81]
	global_load_dword v153, v[80:81], off
	v_or_b32_e32 v80, v22, v59
	v_ashrrev_i32_e32 v81, 31, v80
	v_lshlrev_b64 v[80:81], 15, v[80:81]
	v_lshl_add_u64 v[80:81], v[24:25], 0, v[80:81]
	global_load_dword v154, v[80:81], off
	v_or_b32_e32 v80, v22, v61
	v_ashrrev_i32_e32 v81, 31, v80
	v_lshlrev_b64 v[80:81], 15, v[80:81]
	v_lshl_add_u64 v[80:81], v[24:25], 0, v[80:81]
	global_load_dword v156, v[80:81], off
	v_or_b32_e32 v80, v22, v62
	v_ashrrev_i32_e32 v81, 31, v80
	v_lshlrev_b64 v[80:81], 15, v[80:81]
	v_lshl_add_u64 v[80:81], v[24:25], 0, v[80:81]
	global_load_dword v157, v[80:81], off
	v_or_b32_e32 v80, v22, v63
	v_ashrrev_i32_e32 v81, 31, v80
	v_lshlrev_b64 v[80:81], 15, v[80:81]
	v_lshl_add_u64 v[80:81], v[24:25], 0, v[80:81]
	global_load_dword v158, v[80:81], off
	v_or_b32_e32 v80, v22, v64
	v_ashrrev_i32_e32 v81, 31, v80
	v_lshlrev_b64 v[80:81], 15, v[80:81]
	v_lshl_add_u64 v[80:81], v[24:25], 0, v[80:81]
	global_load_dword v159, v[80:81], off
	v_or_b32_e32 v80, v22, v65
	v_ashrrev_i32_e32 v81, 31, v80
	v_lshlrev_b64 v[80:81], 15, v[80:81]
	v_lshl_add_u64 v[80:81], v[24:25], 0, v[80:81]
	global_load_dword v160, v[80:81], off
	v_or_b32_e32 v80, v22, v66
	v_ashrrev_i32_e32 v81, 31, v80
	v_lshlrev_b64 v[80:81], 15, v[80:81]
	v_lshl_add_u64 v[80:81], v[24:25], 0, v[80:81]
	global_load_dword v161, v[80:81], off
	v_or_b32_e32 v80, v22, v67
	v_ashrrev_i32_e32 v81, 31, v80
	v_lshlrev_b64 v[80:81], 15, v[80:81]
	v_lshl_add_u64 v[24:25], v[24:25], 0, v[80:81]
	v_sub_u32_e32 v80, v78, v23
	v_ashrrev_i32_e32 v23, 31, v22
	v_and_b32_e32 v83, 0xffffff80, v80
	v_lshrrev_b32_e32 v84, 2, v80
	v_lshl_add_u64 v[80:81], v[22:23], 1, v[4:5]
	global_load_dword v162, v[24:25], off
	s_waitcnt vmcnt(0) lgkmcnt(0)
	v_add_u32_e32 v127, v27, v28
	ds_write_b32 v127, v126
	ds_write_b32 v127, v128 offset:264
	ds_write_b32 v127, v129 offset:528
	ds_write_b32 v127, v130 offset:792
	ds_write_b32 v127, v131 offset:1056
	ds_write_b32 v127, v132 offset:1320
	v_add_u32_e32 v134, v27, v35
	ds_write_b32 v134, v133
	ds_write_b32 v134, v135 offset:264
	ds_write_b32 v134, v136 offset:528
	ds_write_b32 v134, v137 offset:792
	ds_write_b32 v134, v138 offset:1056
	ds_write_b32 v134, v139 offset:1320
	v_add_u32_e32 v141, v27, v42
	ds_write_b32 v141, v140
	ds_write_b32 v141, v142 offset:264
	ds_write_b32 v141, v143 offset:528
	ds_write_b32 v141, v144 offset:792
	ds_write_b32 v141, v145 offset:1056
	ds_write_b32 v141, v146 offset:1320
	v_add_u32_e32 v148, v27, v53
	ds_write_b32 v148, v147
	ds_write_b32 v148, v149 offset:264
	ds_write_b32 v148, v150 offset:528
	ds_write_b32 v148, v151 offset:792
	ds_write_b32 v148, v152 offset:1056
	ds_write_b32 v148, v153 offset:1320
	v_add_u32_e32 v155, v27, v60
	ds_write_b32 v155, v154
	ds_write_b32 v155, v156 offset:264
	ds_write_b32 v155, v157 offset:528
	ds_write_b32 v155, v158 offset:792
	ds_write_b32 v155, v159 offset:1056
	ds_write_b32 v155, v160 offset:1320
	ds_write_b32 v155, v161 offset:1584
	ds_write_b32 v155, v162 offset:1848
	v_and_b32_e32 v24, 0x1f00, v75
	v_add_u32_e32 v22, v24, v83
	v_and_b32_e32 v25, 64, v76
	v_and_or_b32 v22, v84, 16, v22
	v_or_b32_e32 v82, v73, v25
	v_or_b32_e32 v23, v22, v25
	v_or3_b32 v22, v82, v22, 32
	v_or_b32_e32 v24, v23, v68
	v_or_b32_e32 v82, v23, v70
	v_ashrrev_i32_e32 v23, 31, v22
	v_ashrrev_i32_e32 v25, 31, v24
	v_or_b32_e32 v84, 32, v24
	v_ashrrev_i32_e32 v83, 31, v82
	v_lshlrev_b64 v[86:87], 11, v[22:23]
	v_lshlrev_b64 v[22:23], 11, v[24:25]
	v_ashrrev_i32_e32 v85, 31, v84
	v_lshlrev_b64 v[24:25], 11, v[82:83]
	v_lshl_add_u64 v[82:83], v[80:81], 0, v[22:23]
	v_lshlrev_b64 v[22:23], 11, v[84:85]
	v_lshl_add_u64 v[88:89], v[80:81], 0, v[24:25]
	v_lshl_add_u64 v[84:85], v[80:81], 0, v[22:23]
	v_lshl_add_u64 v[80:81], v[80:81], 0, v[86:87]
	s_waitcnt lgkmcnt(0)
	ds_read_b32 v2, v69
	ds_read_b32 v22, v69 offset:132
	ds_read_b32 v23, v69 offset:264
	ds_read_b32 v24, v69 offset:396
	ds_read_b32 v25, v69 offset:528
	ds_read_b32 v79, v69 offset:660
	ds_read_b32 v90, v69 offset:792
	ds_read_b32 v91, v69 offset:924
	s_waitcnt lgkmcnt(7)
	v_bfe_u32 v92, v2, 16, 1
	s_waitcnt lgkmcnt(5)
	v_bfe_u32 v94, v23, 16, 1
	s_waitcnt lgkmcnt(3)
	v_bfe_u32 v96, v25, 16, 1
	s_waitcnt lgkmcnt(1)
	v_bfe_u32 v98, v90, 16, 1
	v_bfe_u32 v93, v22, 16, 1
	v_bfe_u32 v95, v24, 16, 1
	v_bfe_u32 v97, v79, 16, 1
	s_waitcnt lgkmcnt(0)
	v_bfe_u32 v99, v91, 16, 1
	v_add3_u32 v2, v2, v92, s56
	v_add3_u32 v23, v23, v94, s56
	v_add3_u32 v25, v25, v96, s56
	v_add3_u32 v90, v90, v98, s56
	v_add3_u32 v22, v22, v93, s56
	v_add3_u32 v24, v24, v95, s56
	v_add3_u32 v79, v79, v97, s56
	v_add3_u32 v91, v91, v99, s56
	v_lshrrev_b32_e32 v2, 16, v2
	v_lshrrev_b32_e32 v23, 16, v23
	v_lshrrev_b32_e32 v25, 16, v25
	v_lshrrev_b32_e32 v90, 16, v90
	v_and_or_b32 v22, v22, s57, v2
	v_and_or_b32 v23, v24, s57, v23
	v_and_or_b32 v24, v79, s57, v25
	v_and_or_b32 v25, v91, s57, v90
	flat_store_dwordx4 v[82:83], v[22:25]
	ds_read_b32 v2, v69 offset:32
	ds_read_b32 v22, v69 offset:164
	ds_read_b32 v23, v69 offset:296
	ds_read_b32 v24, v69 offset:428
	ds_read_b32 v25, v69 offset:560
	ds_read_b32 v79, v69 offset:692
	ds_read_b32 v82, v69 offset:824
	ds_read_b32 v83, v69 offset:956
	s_waitcnt lgkmcnt(0)
	v_bfe_u32 v90, v2, 16, 1
	v_bfe_u32 v92, v23, 16, 1
	v_bfe_u32 v94, v25, 16, 1
	v_bfe_u32 v96, v82, 16, 1
	v_bfe_u32 v91, v22, 16, 1
	v_bfe_u32 v93, v24, 16, 1
	v_bfe_u32 v95, v79, 16, 1
	v_bfe_u32 v97, v83, 16, 1
	v_add3_u32 v2, v2, v90, s56
	v_add3_u32 v23, v23, v92, s56
	v_add3_u32 v25, v25, v94, s56
	v_add3_u32 v82, v82, v96, s56
	v_add3_u32 v22, v22, v91, s56
	v_add3_u32 v24, v24, v93, s56
	v_add3_u32 v79, v79, v95, s56
	v_add3_u32 v83, v83, v97, s56
	v_lshrrev_b32_e32 v2, 16, v2
	v_lshrrev_b32_e32 v23, 16, v23
	v_lshrrev_b32_e32 v25, 16, v25
	v_lshrrev_b32_e32 v82, 16, v82
	v_and_or_b32 v22, v22, s57, v2
	v_and_or_b32 v23, v24, s57, v23
	v_and_or_b32 v24, v79, s57, v25
	v_and_or_b32 v25, v83, s57, v82
	flat_store_dwordx4 v[88:89], v[22:25]
	ds_read_b32 v2, v69 offset:64
	ds_read_b32 v22, v69 offset:196
	ds_read_b32 v23, v69 offset:328
	ds_read_b32 v24, v69 offset:460
	ds_read_b32 v25, v69 offset:592
	ds_read_b32 v79, v69 offset:724
	ds_read_b32 v82, v69 offset:856
	ds_read_b32 v83, v69 offset:988
	s_waitcnt lgkmcnt(0)
	v_bfe_u32 v88, v2, 16, 1
	v_bfe_u32 v90, v23, 16, 1
	v_bfe_u32 v92, v25, 16, 1
	v_bfe_u32 v94, v82, 16, 1
	v_bfe_u32 v89, v22, 16, 1
	v_bfe_u32 v91, v24, 16, 1
	v_bfe_u32 v93, v79, 16, 1
	v_bfe_u32 v95, v83, 16, 1
	v_add3_u32 v2, v2, v88, s56
	v_add3_u32 v23, v23, v90, s56
	v_add3_u32 v25, v25, v92, s56
	v_add3_u32 v82, v82, v94, s56
	v_add3_u32 v22, v22, v89, s56
	v_add3_u32 v24, v24, v91, s56
	v_add3_u32 v79, v79, v93, s56
	v_add3_u32 v83, v83, v95, s56
	v_lshrrev_b32_e32 v2, 16, v2
	v_lshrrev_b32_e32 v23, 16, v23
	v_lshrrev_b32_e32 v25, 16, v25
	v_lshrrev_b32_e32 v82, 16, v82
	v_and_or_b32 v22, v22, s57, v2
	v_and_or_b32 v23, v24, s57, v23
	v_and_or_b32 v24, v79, s57, v25
	v_and_or_b32 v25, v83, s57, v82
	flat_store_dwordx4 v[84:85], v[22:25]
	ds_read_b32 v2, v69 offset:96
	ds_read_b32 v22, v69 offset:228
	ds_read_b32 v23, v69 offset:360
	ds_read_b32 v24, v69 offset:492
	ds_read_b32 v25, v69 offset:624
	ds_read_b32 v79, v69 offset:756
	ds_read_b32 v82, v69 offset:888
	ds_read_b32 v83, v69 offset:1020
	s_waitcnt lgkmcnt(0)
	v_bfe_u32 v84, v2, 16, 1
	v_bfe_u32 v88, v23, 16, 1
	v_bfe_u32 v90, v25, 16, 1
	v_bfe_u32 v92, v82, 16, 1
	v_bfe_u32 v85, v22, 16, 1
	v_bfe_u32 v89, v24, 16, 1
	v_bfe_u32 v91, v79, 16, 1
	v_bfe_u32 v93, v83, 16, 1
	v_add3_u32 v2, v2, v84, s56
	v_add3_u32 v23, v23, v88, s56
	v_add3_u32 v25, v25, v90, s56
	v_add3_u32 v82, v82, v92, s56
	v_add3_u32 v22, v22, v85, s56
	v_add3_u32 v24, v24, v89, s56
	v_add3_u32 v79, v79, v91, s56
	v_add3_u32 v83, v83, v93, s56
	v_lshrrev_b32_e32 v2, 16, v2
	v_lshrrev_b32_e32 v23, 16, v23
	v_lshrrev_b32_e32 v25, 16, v25
	v_lshrrev_b32_e32 v82, 16, v82
	v_and_or_b32 v22, v22, s57, v2
	v_and_or_b32 v23, v24, s57, v23
	v_and_or_b32 v24, v79, s57, v25
	v_and_or_b32 v25, v83, s57, v82
	flat_store_dwordx4 v[80:81], v[22:25]
	s_waitcnt lgkmcnt(0)
	s_branch .LBB0_9
